# baseline (speedup 1.0000x reference)
; DEV float bf2f(u16 h) { return __uint_as_float(((uint32_t)h) << 16); }
; DEV void gemm_tile(const u16* __restrict__ A, const u16* __restrict__ Bt, u16* __restrict__ C, int N, int K,
;                    int brow, int bcol, unsigned char* smem, int epi, const GateEpi& ge) {
;     ...
;     const int pm = brow >> 8, pn = bcol >> 8;
;     float w0[2], w1[2], w2[2], bs[2];
; #pragma unroll
;     for (int n = 0; n < 2; ++n) {
;       const int cg = pn * 128 + wc * 32 + n * 16 + fr2;
;       w0[n] = ge.cw[cg]; w1[n] = ge.cw[DFF + cg]; w2[n] = ge.cw[2 * DFF + cg]; bs[n] = ge.cb[cg];
;     }
; #pragma unroll
;     for (int ai = 0; ai < 2; ++ai)
; #pragma unroll
;       for (int m = 0; m < 4; ++m) {
;         const int R0 = ai * 128 + wr * 64 + m * 16 + fq2 * 4;
; #pragma unroll
;         for (int n = 0; n < 2; ++n) {
;           const int cl = wc * 32 + n * 16 + fr2, cg = pn * 128 + cl;
;           float am2 = 0.f, am1 = 0.f;
;           if (R0 > 0) { am2 = bf2f(sAt[(R0 - 2) * AS + cl]); am1 = bf2f(sAt[(R0 - 1) * AS + cl]); }
; #pragma unroll
;           for (int j = 0; j < 4; ++j) {
;             const float a0 = acc[ai][0][m][n][j], b0 = acc[ai][1][m][n][j];
;             if (R0 > 0 || j >= 2) {
;               const float gv = gelu_tanh(bs[n] + w0[n] * am2 + w1[n] * am1 + w2[n] * a0) * b0;
.Lg_gate:
	s_add_i32 s62, s1, 0x21000
	v_lshlrev_b32_e32 v154, 5, v181
	v_add_u32_e32 v154, s62, v154
	ds_read_b128 v[184:187], v154 offset:0
	ds_read_b128 v[188:191], v154 offset:16
	ds_read_b128 v[192:195], v154 offset:128
	ds_read_b128 v[196:199], v154 offset:144
	ds_read_b128 v[200:203], v154 offset:256
	ds_read_b128 v[204:207], v154 offset:272
	ds_read_b128 v[208:211], v154 offset:384
	ds_read_b128 v[212:215], v154 offset:400
	s_lshl_b32 s0, s47, 5
	s_and_b32 s0, s0, 0xffffff00
	s_lshl_b32 s1, s50, 6
	s_add_i32 s28, s0, s1
	s_add_i32 s0, s51, s49
	s_mul_hi_u32 s1, s0, s85
	s_mul_i32 s0, s0, s85
	s_add_u32 s0, s0, s28
	s_addc_u32 s1, s1, 0
	s_add_u32 s0, s80, s0
	s_addc_u32 s1, s81, s1
	s_ashr_i32 s4, s49, 8
	s_mul_i32 s4, s4, 0x5800
	s_add_i32 s4, s4, s28
	s_add_u32 s6, s22, s4
	s_addc_u32 s7, s23, 0
	s_add_u32 s54, s82, s4
	s_addc_u32 s55, s83, 0
	s_sub_u32 s54, s54, 0x26800
	s_subb_u32 s55, s55, 0
	s_add_u32 s4, s20, s4
	s_addc_u32 s5, s21, 0
	v_mul_u32_u24_e32 v153, 0x2c00, v180
	v_lshl_add_u32 v153, v181, 4, v153
	v_and_b32_e32 v157, 1, v180
	v_lshlrev_b32_e32 v157, 5, v157
	v_lshl_add_u32 v157, v181, 6, v157
	s_lshl_b32 s62, s50, 8
	s_add_i32 s62, s62, 0x20000
	v_add_u32_e32 v157, s62, v157
	s_lshl_b32 s62, s34, 10
	v_add_u32_e32 v158, s62, v157
	s_add_i32 s62, s34, 3
	s_and_b32 s62, s62, 3
	s_lshl_b32 s62, s62, 10
	v_add_u32_e32 v159, s62, v157
	s_mov_b32 s52, 0xbdd2d3e8
	s_mov_b32 s53, 0xbdd2d3e8
	s_mov_b32 s94, 1.0
	s_mov_b32 s95, 1.0
	s_mov_b32 exec_lo, 0xc000c000
	s_mov_b32 exec_hi, 0xc000c000
	ds_write_b128 v158, v[100:103]
	ds_write_b128 v158, v[96:99] offset:16
	ds_write_b128 v158, v[4:7] offset:2048
	ds_write_b128 v158, v[0:3] offset:2064
	s_mov_b64 exec, -1
	s_waitcnt lgkmcnt(0)
	s_barrier
	ds_read_b128 v[232:235], v159
	ds_read_b128 v[236:239], v159 offset:16
	s_add_i32 s62, s34, 1
	s_lshl_b32 s62, s62, 10
	v_add_u32_e32 v156, s62, v157
	v_cmp_eq_u32_e32 vcc, 0, v180
	s_nop 1
	v_cndmask_b32_e32 v216, 0, v192, vcc
	v_cndmask_b32_e32 v217, 0, v193, vcc
	v_cndmask_b32_e32 v218, 0, v194, vcc
	v_cndmask_b32_e32 v219, 0, v195, vcc
	v_cndmask_b32_e32 v220, 0, v196, vcc
	v_cndmask_b32_e32 v221, 0, v197, vcc
	v_cndmask_b32_e32 v222, 0, v198, vcc
	v_cndmask_b32_e32 v223, 0, v199, vcc
	v_cmp_gt_u32_e32 vcc, 2, v180
	s_nop 1
	v_cndmask_b32_e32 v224, 0, v184, vcc
	v_cndmask_b32_e32 v225, 0, v185, vcc
	v_cndmask_b32_e32 v226, 0, v186, vcc
	v_cndmask_b32_e32 v227, 0, v187, vcc
	v_cndmask_b32_e32 v228, 0, v188, vcc
	v_cndmask_b32_e32 v229, 0, v189, vcc
	v_cndmask_b32_e32 v230, 0, v190, vcc
	v_cndmask_b32_e32 v231, 0, v191, vcc
	v_mov_b32_e32 v180, v163
	v_mov_b32_e32 v181, v163
	s_waitcnt lgkmcnt(0)
	v_pk_fma_f32 v[240:241], v[200:201], v[124:125], v[208:209]
	v_pk_fma_f32 v[242:243], v[202:203], v[126:127], v[210:211]
	v_pk_fma_f32 v[244:245], v[204:205], v[120:121], v[212:213]
	v_pk_fma_f32 v[246:247], v[206:207], v[122:123], v[214:215]
	v_fmac_f32_dpp v240, v124, v192 row_shr:1 row_mask:0xf bank_mask:0xf
	v_fmac_f32_dpp v241, v125, v193 row_shr:1 row_mask:0xf bank_mask:0xf
	v_fmac_f32_dpp v242, v126, v194 row_shr:1 row_mask:0xf bank_mask:0xf
	v_fmac_f32_dpp v243, v127, v195 row_shr:1 row_mask:0xf bank_mask:0xf
	v_fmac_f32_dpp v244, v120, v196 row_shr:1 row_mask:0xf bank_mask:0xf
	v_fmac_f32_dpp v245, v121, v197 row_shr:1 row_mask:0xf bank_mask:0xf
	v_fmac_f32_dpp v246, v122, v198 row_shr:1 row_mask:0xf bank_mask:0xf
	v_fmac_f32_dpp v247, v123, v199 row_shr:1 row_mask:0xf bank_mask:0xf
	v_fmac_f32_dpp v240, v232, v216 row_ror:1 row_mask:0xf bank_mask:0xf
	v_fmac_f32_dpp v241, v233, v217 row_ror:1 row_mask:0xf bank_mask:0xf
	v_fmac_f32_dpp v242, v234, v218 row_ror:1 row_mask:0xf bank_mask:0xf
	v_fmac_f32_dpp v243, v235, v219 row_ror:1 row_mask:0xf bank_mask:0xf
	v_fmac_f32_dpp v244, v236, v220 row_ror:1 row_mask:0xf bank_mask:0xf
	v_fmac_f32_dpp v245, v237, v221 row_ror:1 row_mask:0xf bank_mask:0xf
	v_fmac_f32_dpp v246, v238, v222 row_ror:1 row_mask:0xf bank_mask:0xf
	v_fmac_f32_dpp v247, v239, v223 row_ror:1 row_mask:0xf bank_mask:0xf
	v_fmac_f32_dpp v240, v124, v184 row_shr:2 row_mask:0xf bank_mask:0xf
	v_fmac_f32_dpp v241, v125, v185 row_shr:2 row_mask:0xf bank_mask:0xf
	v_fmac_f32_dpp v242, v126, v186 row_shr:2 row_mask:0xf bank_mask:0xf
	v_fmac_f32_dpp v243, v127, v187 row_shr:2 row_mask:0xf bank_mask:0xf
	v_fmac_f32_dpp v244, v120, v188 row_shr:2 row_mask:0xf bank_mask:0xf
	v_fmac_f32_dpp v245, v121, v189 row_shr:2 row_mask:0xf bank_mask:0xf
	v_fmac_f32_dpp v246, v122, v190 row_shr:2 row_mask:0xf bank_mask:0xf
	v_fmac_f32_dpp v247, v123, v191 row_shr:2 row_mask:0xf bank_mask:0xf
	v_fmac_f32_dpp v240, v232, v224 row_ror:2 row_mask:0xf bank_mask:0xf
	v_fmac_f32_dpp v241, v233, v225 row_ror:2 row_mask:0xf bank_mask:0xf
	v_fmac_f32_dpp v242, v234, v226 row_ror:2 row_mask:0xf bank_mask:0xf
	v_fmac_f32_dpp v243, v235, v227 row_ror:2 row_mask:0xf bank_mask:0xf
	v_fmac_f32_dpp v244, v236, v228 row_ror:2 row_mask:0xf bank_mask:0xf
; DEV float bf2f(u16 h) { return __uint_as_float(((uint32_t)h) << 16); }
; DEV float gelu_tanh(float x) {
;   const float e = __builtin_amdgcn_exp2f(x * __builtin_fmaf(x * x, -0.10294324f, -2.3022082f));
;   return x * __builtin_amdgcn_rcpf(1.0f + e);
; }
; DEV void gemm_tile(const u16* __restrict__ A, const u16* __restrict__ Bt, u16* __restrict__ C, int N, int K,
;                    int brow, int bcol, unsigned char* smem, int epi, const GateEpi& ge) {
;     ...
;         const int R0 = ai * 128 + wr * 64 + m * 16 + fq2 * 4;
; #pragma unroll
;         for (int n = 0; n < 2; ++n) {
;           const int cl = wc * 32 + n * 16 + fr2, cg = pn * 128 + cl;
;           float am2 = 0.f, am1 = 0.f;
;           if (R0 > 0) { am2 = bf2f(sAt[(R0 - 2) * AS + cl]); am1 = bf2f(sAt[(R0 - 1) * AS + cl]); }
; #pragma unroll
;           for (int j = 0; j < 4; ++j) {
;             const float a0 = acc[ai][0][m][n][j], b0 = acc[ai][1][m][n][j];
;             if (R0 > 0 || j >= 2) {
;               const float gv = gelu_tanh(bs[n] + w0[n] * am2 + w1[n] * am1 + w2[n] * a0) * b0;
;               ge.g[(size_t)(brow + R0 + j) * DFF + cg] = f2bf(gv);
;             } else {
;               ge.first_a[((size_t)pm * 2 + j) * DFF + cg] = sAt[(R0 + j) * AS + cl];
;               ge.first_b[((size_t)pm * 2 + j) * DFF + cg] = f2bf(b0);
;             }
;             if (R0 == 252 && j >= 2) ge.halo_a[((size_t)pm * 2 + (j - 2)) * DFF + cg] = sAt[(R0 + j) * AS + cl];
;             am2 = am1; am1 = a0;
	v_fmac_f32_dpp v245, v237, v229 row_ror:2 row_mask:0xf bank_mask:0xf
	v_fmac_f32_dpp v246, v238, v230 row_ror:2 row_mask:0xf bank_mask:0xf
	v_fmac_f32_dpp v247, v239, v231 row_ror:2 row_mask:0xf bank_mask:0xf
	v_fmac_f32_dpp v157, v232, v224 row_shr:1 row_mask:0xf bank_mask:0xf
	v_fmac_f32_dpp v157, v233, v225 row_shr:1 row_mask:0xf bank_mask:0xf
	v_fmac_f32_dpp v157, v234, v226 row_shr:1 row_mask:0xf bank_mask:0xf
	v_fmac_f32_dpp v157, v235, v227 row_shr:1 row_mask:0xf bank_mask:0xf
	v_fmac_f32_dpp v157, v236, v228 row_shr:1 row_mask:0xf bank_mask:0xf
	v_fmac_f32_dpp v157, v237, v229 row_shr:1 row_mask:0xf bank_mask:0xf
	v_fmac_f32_dpp v157, v238, v230 row_shr:1 row_mask:0xf bank_mask:0xf
	v_fmac_f32_dpp v157, v239, v231 row_shr:1 row_mask:0xf bank_mask:0xf
	v_fmac_f32_dpp v157, v232, v224 row_shr:1 row_mask:0xf bank_mask:0xf
	v_fmac_f32_dpp v157, v233, v225 row_shr:1 row_mask:0xf bank_mask:0xf
	v_fmac_f32_dpp v157, v234, v226 row_shr:1 row_mask:0xf bank_mask:0xf
	v_fmac_f32_dpp v157, v235, v227 row_shr:1 row_mask:0xf bank_mask:0xf
	v_fmac_f32_dpp v157, v236, v228 row_shr:1 row_mask:0xf bank_mask:0xf
	v_fmac_f32_dpp v157, v237, v229 row_shr:1 row_mask:0xf bank_mask:0xf
	v_fmac_f32_dpp v157, v238, v230 row_shr:1 row_mask:0xf bank_mask:0xf
	v_fmac_f32_dpp v157, v239, v231 row_shr:1 row_mask:0xf bank_mask:0xf
	v_fmac_f32_dpp v157, v232, v224 row_shr:1 row_mask:0xf bank_mask:0xf
	v_fmac_f32_dpp v157, v233, v225 row_shr:1 row_mask:0xf bank_mask:0xf
	v_fmac_f32_dpp v157, v234, v226 row_shr:1 row_mask:0xf bank_mask:0xf
	v_fmac_f32_dpp v157, v235, v227 row_shr:1 row_mask:0xf bank_mask:0xf
	v_fmac_f32_dpp v157, v236, v228 row_shr:1 row_mask:0xf bank_mask:0xf
	v_fmac_f32_dpp v157, v237, v229 row_shr:1 row_mask:0xf bank_mask:0xf
	v_fmac_f32_dpp v157, v238, v230 row_shr:1 row_mask:0xf bank_mask:0xf
	v_fmac_f32_dpp v157, v239, v231 row_shr:1 row_mask:0xf bank_mask:0xf
	v_fmac_f32_dpp v157, v232, v224 row_shr:1 row_mask:0xf bank_mask:0xf
	v_fmac_f32_dpp v157, v233, v225 row_shr:1 row_mask:0xf bank_mask:0xf
	v_fmac_f32_dpp v157, v234, v226 row_shr:1 row_mask:0xf bank_mask:0xf
	v_fmac_f32_dpp v157, v235, v227 row_shr:1 row_mask:0xf bank_mask:0xf
	v_fmac_f32_dpp v157, v236, v228 row_shr:1 row_mask:0xf bank_mask:0xf
	v_fmac_f32_dpp v157, v237, v229 row_shr:1 row_mask:0xf bank_mask:0xf
	v_fmac_f32_dpp v157, v238, v230 row_shr:1 row_mask:0xf bank_mask:0xf
	v_fmac_f32_dpp v157, v239, v231 row_shr:1 row_mask:0xf bank_mask:0xf
	ds_read_b128 v[232:235], v156
	ds_read_b128 v[236:239], v156 offset:16
	v_pk_mul_f32 v[248:249], v[240:241], v[240:241]
	v_pk_mul_f32 v[250:251], v[242:243], v[242:243]
	v_pk_mul_f32 v[182:183], v[244:245], v[244:245]
	v_pk_mul_f32 v[154:155], v[246:247], v[246:247]
	v_pk_fma_f32 v[248:249], v[248:249], s[52:53], v[180:181]
	v_pk_fma_f32 v[250:251], v[250:251], s[52:53], v[180:181]
	v_pk_fma_f32 v[182:183], v[182:183], s[52:53], v[180:181]
	v_pk_fma_f32 v[154:155], v[154:155], s[52:53], v[180:181]
	v_pk_mul_f32 v[248:249], v[240:241], v[248:249]
	v_pk_mul_f32 v[250:251], v[242:243], v[250:251]
	v_pk_mul_f32 v[182:183], v[244:245], v[182:183]
	v_pk_mul_f32 v[154:155], v[246:247], v[154:155]
	v_exp_f32_e32 v248, v248
	v_exp_f32_e32 v249, v249
	v_exp_f32_e32 v250, v250
	v_exp_f32_e32 v251, v251
	v_exp_f32_e32 v182, v182
	v_exp_f32_e32 v183, v183
	v_exp_f32_e32 v154, v154
	v_exp_f32_e32 v155, v155
	v_pk_add_f32 v[248:249], v[248:249], s[94:95]
	v_pk_add_f32 v[250:251], v[250:251], s[94:95]
	v_pk_add_f32 v[182:183], v[182:183], s[94:95]
	v_pk_add_f32 v[154:155], v[154:155], s[94:95]
	v_rcp_f32_e32 v248, v248
	v_rcp_f32_e32 v249, v249
	v_rcp_f32_e32 v250, v250
	v_rcp_f32_e32 v251, v251
	v_rcp_f32_e32 v182, v182
	v_rcp_f32_e32 v183, v183
	v_rcp_f32_e32 v154, v154
	v_rcp_f32_e32 v155, v155
	v_pk_mul_f32 v[240:241], v[240:241], v[248:249]
	v_pk_mul_f32 v[242:243], v[242:243], v[250:251]
	v_pk_mul_f32 v[244:245], v[244:245], v[182:183]
	v_pk_mul_f32 v[246:247], v[246:247], v[154:155]
	v_pk_mul_f32 v[240:241], v[240:241], v[84:85]
	v_pk_mul_f32 v[242:243], v[242:243], v[86:87]
	v_pk_mul_f32 v[244:245], v[244:245], v[68:69]
	v_pk_mul_f32 v[246:247], v[246:247], v[70:71]
	v_cvt_pk_bf16_f32 v248, v240, v241
	v_cvt_pk_bf16_f32 v249, v242, v243
	v_cvt_pk_bf16_f32 v250, v244, v245
	v_cvt_pk_bf16_f32 v251, v246, v247
	s_cmp_lg_u32 s34, 0
	s_cbranch_scc1 .Lgate_plain00_0
	s_mov_b32 exec_lo, 0x30003
	s_mov_b32 exec_hi, 0x30003
	v_cvt_pk_bf16_f32 v240, v124, v125
	v_cvt_pk_bf16_f32 v241, v126, v127
	v_cvt_pk_bf16_f32 v242, v120, v121
	v_cvt_pk_bf16_f32 v243, v122, v123
	v_cvt_pk_bf16_f32 v244, v84, v85
	v_cvt_pk_bf16_f32 v245, v86, v87
	v_cvt_pk_bf16_f32 v246, v68, v69
	v_cvt_pk_bf16_f32 v247, v70, v71
	global_store_dwordx4 v153, v[240:243], s[4:5]
	global_store_dwordx4 v153, v[244:247], s[6:7]
	s_not_b64 exec, exec
	global_store_dwordx4 v153, v[248:251], s[0:1]
	s_mov_b64 exec, -1
	s_branch .Lgate_done00_0

; DEV float bf2f(u16 h) { return __uint_as_float(((uint32_t)h) << 16); }
; DEV void gemm_tile(const u16* __restrict__ A, const u16* __restrict__ Bt, u16* __restrict__ C, int N, int K,
;                    int brow, int bcol, unsigned char* smem, int epi, const GateEpi& ge) {
;     ...
; #pragma unroll
;     for (int ai = 0; ai < 2; ++ai)
; #pragma unroll
;       for (int m = 0; m < 4; ++m) {
;         const int R0 = ai * 128 + wr * 64 + m * 16 + fq2 * 4;
; #pragma unroll
;         for (int n = 0; n < 2; ++n) {
;           const int cl = wc * 32 + n * 16 + fr2, cg = pn * 128 + cl;
;           float am2 = 0.f, am1 = 0.f;
;           if (R0 > 0) { am2 = bf2f(sAt[(R0 - 2) * AS + cl]); am1 = bf2f(sAt[(R0 - 1) * AS + cl]); }
; #pragma unroll
;           for (int j = 0; j < 4; ++j) {
;             const float a0 = acc[ai][0][m][n][j], b0 = acc[ai][1][m][n][j];
;             if (R0 > 0 || j >= 2) {
;               const float gv = gelu_tanh(bs[n] + w0[n] * am2 + w1[n] * am1 + w2[n] * a0) * b0;
;               ge.g[(size_t)(brow + R0 + j) * DFF + cg] = f2bf(gv);
;             } else {
;               ge.first_a[((size_t)pm * 2 + j) * DFF + cg] = sAt[(R0 + j) * AS + cl];
;               ge.first_b[((size_t)pm * 2 + j) * DFF + cg] = f2bf(b0);
;             }
;             if (R0 == 252 && j >= 2) ge.halo_a[((size_t)pm * 2 + (j - 2)) * DFF + cg] = sAt[(R0 + j) * AS + cl];
;             am2 = am1; am1 = a0;
;           }
;         }
;         __builtin_amdgcn_sched_barrier(0);
;       }
.Lgate_done00_0:
	s_add_u32 s0, s0, 0x2c000
	s_addc_u32 s1, s1, 0
	v_pk_fma_f32 v[240:241], v[200:201], v[116:117], v[208:209]
	v_pk_fma_f32 v[242:243], v[202:203], v[118:119], v[210:211]
	v_pk_fma_f32 v[244:245], v[204:205], v[112:113], v[212:213]
	v_pk_fma_f32 v[246:247], v[206:207], v[114:115], v[214:215]
	v_fmac_f32_dpp v240, v116, v192 row_shr:1 row_mask:0xf bank_mask:0xf
	v_fmac_f32_dpp v241, v117, v193 row_shr:1 row_mask:0xf bank_mask:0xf
	v_fmac_f32_dpp v242, v118, v194 row_shr:1 row_mask:0xf bank_mask:0xf
	v_fmac_f32_dpp v243, v119, v195 row_shr:1 row_mask:0xf bank_mask:0xf
	v_fmac_f32_dpp v244, v112, v196 row_shr:1 row_mask:0xf bank_mask:0xf
	v_fmac_f32_dpp v245, v113, v197 row_shr:1 row_mask:0xf bank_mask:0xf
	v_fmac_f32_dpp v246, v114, v198 row_shr:1 row_mask:0xf bank_mask:0xf
	v_fmac_f32_dpp v247, v115, v199 row_shr:1 row_mask:0xf bank_mask:0xf
	v_fmac_f32_dpp v240, v124, v216 row_ror:1 row_mask:0xf bank_mask:0xf
	v_fmac_f32_dpp v241, v125, v217 row_ror:1 row_mask:0xf bank_mask:0xf
	v_fmac_f32_dpp v242, v126, v218 row_ror:1 row_mask:0xf bank_mask:0xf
	v_fmac_f32_dpp v243, v127, v219 row_ror:1 row_mask:0xf bank_mask:0xf
	v_fmac_f32_dpp v244, v120, v220 row_ror:1 row_mask:0xf bank_mask:0xf
	v_fmac_f32_dpp v245, v121, v221 row_ror:1 row_mask:0xf bank_mask:0xf
	v_fmac_f32_dpp v246, v122, v222 row_ror:1 row_mask:0xf bank_mask:0xf
	v_fmac_f32_dpp v247, v123, v223 row_ror:1 row_mask:0xf bank_mask:0xf
	v_fmac_f32_dpp v240, v116, v184 row_shr:2 row_mask:0xf bank_mask:0xf
	v_fmac_f32_dpp v241, v117, v185 row_shr:2 row_mask:0xf bank_mask:0xf
	v_fmac_f32_dpp v242, v118, v186 row_shr:2 row_mask:0xf bank_mask:0xf
	v_fmac_f32_dpp v243, v119, v187 row_shr:2 row_mask:0xf bank_mask:0xf
	v_fmac_f32_dpp v244, v112, v188 row_shr:2 row_mask:0xf bank_mask:0xf
	v_fmac_f32_dpp v245, v113, v189 row_shr:2 row_mask:0xf bank_mask:0xf
	v_fmac_f32_dpp v246, v114, v190 row_shr:2 row_mask:0xf bank_mask:0xf
	v_fmac_f32_dpp v247, v115, v191 row_shr:2 row_mask:0xf bank_mask:0xf
	v_fmac_f32_dpp v240, v124, v224 row_ror:2 row_mask:0xf bank_mask:0xf
	v_fmac_f32_dpp v241, v125, v225 row_ror:2 row_mask:0xf bank_mask:0xf
	v_fmac_f32_dpp v242, v126, v226 row_ror:2 row_mask:0xf bank_mask:0xf
	v_fmac_f32_dpp v243, v127, v227 row_ror:2 row_mask:0xf bank_mask:0xf
	v_fmac_f32_dpp v244, v120, v228 row_ror:2 row_mask:0xf bank_mask:0xf
	v_fmac_f32_dpp v245, v121, v229 row_ror:2 row_mask:0xf bank_mask:0xf
	v_fmac_f32_dpp v246, v122, v230 row_ror:2 row_mask:0xf bank_mask:0xf
	v_fmac_f32_dpp v247, v123, v231 row_ror:2 row_mask:0xf bank_mask:0xf
	v_fmac_f32_dpp v157, v124, v224 row_shr:1 row_mask:0xf bank_mask:0xf
	v_fmac_f32_dpp v157, v125, v225 row_shr:1 row_mask:0xf bank_mask:0xf
	v_fmac_f32_dpp v157, v126, v226 row_shr:1 row_mask:0xf bank_mask:0xf
	v_fmac_f32_dpp v157, v127, v227 row_shr:1 row_mask:0xf bank_mask:0xf
	v_fmac_f32_dpp v157, v120, v228 row_shr:1 row_mask:0xf bank_mask:0xf
	v_fmac_f32_dpp v157, v121, v229 row_shr:1 row_mask:0xf bank_mask:0xf
	v_fmac_f32_dpp v157, v122, v230 row_shr:1 row_mask:0xf bank_mask:0xf
	v_fmac_f32_dpp v157, v123, v231 row_shr:1 row_mask:0xf bank_mask:0xf
	v_fmac_f32_dpp v157, v124, v224 row_shr:1 row_mask:0xf bank_mask:0xf
	v_fmac_f32_dpp v157, v125, v225 row_shr:1 row_mask:0xf bank_mask:0xf
	v_fmac_f32_dpp v157, v126, v226 row_shr:1 row_mask:0xf bank_mask:0xf
	v_fmac_f32_dpp v157, v127, v227 row_shr:1 row_mask:0xf bank_mask:0xf
	v_fmac_f32_dpp v157, v120, v228 row_shr:1 row_mask:0xf bank_mask:0xf
	v_fmac_f32_dpp v157, v121, v229 row_shr:1 row_mask:0xf bank_mask:0xf
	v_fmac_f32_dpp v157, v122, v230 row_shr:1 row_mask:0xf bank_mask:0xf
	v_fmac_f32_dpp v157, v123, v231 row_shr:1 row_mask:0xf bank_mask:0xf
	v_fmac_f32_dpp v157, v124, v224 row_shr:1 row_mask:0xf bank_mask:0xf
	v_fmac_f32_dpp v157, v125, v225 row_shr:1 row_mask:0xf bank_mask:0xf
	v_fmac_f32_dpp v157, v126, v226 row_shr:1 row_mask:0xf bank_mask:0xf
	v_fmac_f32_dpp v157, v127, v227 row_shr:1 row_mask:0xf bank_mask:0xf
	v_fmac_f32_dpp v157, v120, v228 row_shr:1 row_mask:0xf bank_mask:0xf
	v_fmac_f32_dpp v157, v121, v229 row_shr:1 row_mask:0xf bank_mask:0xf
	v_fmac_f32_dpp v157, v122, v230 row_shr:1 row_mask:0xf bank_mask:0xf
	v_fmac_f32_dpp v157, v123, v231 row_shr:1 row_mask:0xf bank_mask:0xf
	v_fmac_f32_dpp v157, v124, v224 row_shr:1 row_mask:0xf bank_mask:0xf
	v_fmac_f32_dpp v157, v125, v225 row_shr:1 row_mask:0xf bank_mask:0xf
	v_fmac_f32_dpp v157, v126, v226 row_shr:1 row_mask:0xf bank_mask:0xf
	v_fmac_f32_dpp v157, v127, v227 row_shr:1 row_mask:0xf bank_mask:0xf
	v_fmac_f32_dpp v157, v120, v228 row_shr:1 row_mask:0xf bank_mask:0xf
	v_fmac_f32_dpp v157, v121, v229 row_shr:1 row_mask:0xf bank_mask:0xf
	v_fmac_f32_dpp v157, v122, v230 row_shr:1 row_mask:0xf bank_mask:0xf
	v_fmac_f32_dpp v157, v123, v231 row_shr:1 row_mask:0xf bank_mask:0xf
	v_pk_mul_f32 v[248:249], v[240:241], v[240:241]
	v_pk_mul_f32 v[250:251], v[242:243], v[242:243]
	v_pk_mul_f32 v[182:183], v[244:245], v[244:245]
	v_pk_mul_f32 v[154:155], v[246:247], v[246:247]
	v_pk_fma_f32 v[248:249], v[248:249], s[52:53], v[180:181]
	v_pk_fma_f32 v[250:251], v[250:251], s[52:53], v[180:181]
	v_pk_fma_f32 v[182:183], v[182:183], s[52:53], v[180:181]
	v_pk_fma_f32 v[154:155], v[154:155], s[52:53], v[180:181]
	v_pk_mul_f32 v[248:249], v[240:241], v[248:249]
	v_pk_mul_f32 v[250:251], v[242:243], v[250:251]
	v_pk_mul_f32 v[182:183], v[244:245], v[182:183]
	v_pk_mul_f32 v[154:155], v[246:247], v[154:155]
	v_exp_f32_e32 v248, v248
	v_exp_f32_e32 v249, v249
	v_exp_f32_e32 v250, v250
	v_exp_f32_e32 v251, v251
	v_exp_f32_e32 v182, v182
	v_exp_f32_e32 v183, v183
	v_exp_f32_e32 v154, v154
	v_exp_f32_e32 v155, v155
; DEV float bf2f(u16 h) { return __uint_as_float(((uint32_t)h) << 16); }
; DEV void gemm_tile(const u16* __restrict__ A, const u16* __restrict__ Bt, u16* __restrict__ C, int N, int K,
;                    int brow, int bcol, unsigned char* smem, int epi, const GateEpi& ge) {
;     ...
; #pragma unroll
;     for (int ai = 0; ai < 2; ++ai)
; #pragma unroll
;       for (int m = 0; m < 4; ++m) {
;         const int R0 = ai * 128 + wr * 64 + m * 16 + fq2 * 4;
; #pragma unroll
;         for (int n = 0; n < 2; ++n) {
;           const int cl = wc * 32 + n * 16 + fr2, cg = pn * 128 + cl;
;           float am2 = 0.f, am1 = 0.f;
;           if (R0 > 0) { am2 = bf2f(sAt[(R0 - 2) * AS + cl]); am1 = bf2f(sAt[(R0 - 1) * AS + cl]); }
; #pragma unroll
;           for (int j = 0; j < 4; ++j) {
;             const float a0 = acc[ai][0][m][n][j], b0 = acc[ai][1][m][n][j];
;             if (R0 > 0 || j >= 2) {
;               const float gv = gelu_tanh(bs[n] + w0[n] * am2 + w1[n] * am1 + w2[n] * a0) * b0;
;               ge.g[(size_t)(brow + R0 + j) * DFF + cg] = f2bf(gv);
;             } else {
;               ge.first_a[((size_t)pm * 2 + j) * DFF + cg] = sAt[(R0 + j) * AS + cl];
;               ge.first_b[((size_t)pm * 2 + j) * DFF + cg] = f2bf(b0);
;             }
;             if (R0 == 252 && j >= 2) ge.halo_a[((size_t)pm * 2 + (j - 2)) * DFF + cg] = sAt[(R0 + j) * AS + cl];
;             am2 = am1; am1 = a0;
;           }
;         }
;         __builtin_amdgcn_sched_barrier(0);
;       }
	v_pk_add_f32 v[248:249], v[248:249], s[94:95]
	v_pk_add_f32 v[250:251], v[250:251], s[94:95]
	v_pk_add_f32 v[182:183], v[182:183], s[94:95]
	v_pk_add_f32 v[154:155], v[154:155], s[94:95]
	v_rcp_f32_e32 v248, v248
	v_rcp_f32_e32 v249, v249
	v_rcp_f32_e32 v250, v250
	v_rcp_f32_e32 v251, v251
	v_rcp_f32_e32 v182, v182
	v_rcp_f32_e32 v183, v183
	v_rcp_f32_e32 v154, v154
	v_rcp_f32_e32 v155, v155
	v_pk_mul_f32 v[240:241], v[240:241], v[248:249]
	v_pk_mul_f32 v[242:243], v[242:243], v[250:251]
	v_pk_mul_f32 v[244:245], v[244:245], v[182:183]
	v_pk_mul_f32 v[246:247], v[246:247], v[154:155]
	v_pk_mul_f32 v[240:241], v[240:241], v[52:53]
	v_pk_mul_f32 v[242:243], v[242:243], v[54:55]
	v_pk_mul_f32 v[244:245], v[244:245], v[48:49]
	v_pk_mul_f32 v[246:247], v[246:247], v[50:51]
	v_cvt_pk_bf16_f32 v248, v240, v241
	v_cvt_pk_bf16_f32 v249, v242, v243
	v_cvt_pk_bf16_f32 v250, v244, v245
	v_cvt_pk_bf16_f32 v251, v246, v247
	global_store_dwordx4 v153, v[248:251], s[0:1]
	s_add_u32 s0, s0, 0x2c000
	s_addc_u32 s1, s1, 0
	v_pk_fma_f32 v[240:241], v[200:201], v[108:109], v[208:209]
	v_pk_fma_f32 v[242:243], v[202:203], v[110:111], v[210:211]
	v_pk_fma_f32 v[244:245], v[204:205], v[104:105], v[212:213]
	v_pk_fma_f32 v[246:247], v[206:207], v[106:107], v[214:215]
	v_fmac_f32_dpp v240, v108, v192 row_shr:1 row_mask:0xf bank_mask:0xf
	v_fmac_f32_dpp v241, v109, v193 row_shr:1 row_mask:0xf bank_mask:0xf
	v_fmac_f32_dpp v242, v110, v194 row_shr:1 row_mask:0xf bank_mask:0xf
	v_fmac_f32_dpp v243, v111, v195 row_shr:1 row_mask:0xf bank_mask:0xf
	v_fmac_f32_dpp v244, v104, v196 row_shr:1 row_mask:0xf bank_mask:0xf
	v_fmac_f32_dpp v245, v105, v197 row_shr:1 row_mask:0xf bank_mask:0xf
	v_fmac_f32_dpp v246, v106, v198 row_shr:1 row_mask:0xf bank_mask:0xf
	v_fmac_f32_dpp v247, v107, v199 row_shr:1 row_mask:0xf bank_mask:0xf
	v_fmac_f32_dpp v240, v116, v216 row_ror:1 row_mask:0xf bank_mask:0xf
	v_fmac_f32_dpp v241, v117, v217 row_ror:1 row_mask:0xf bank_mask:0xf
	v_fmac_f32_dpp v242, v118, v218 row_ror:1 row_mask:0xf bank_mask:0xf
	v_fmac_f32_dpp v243, v119, v219 row_ror:1 row_mask:0xf bank_mask:0xf
	v_fmac_f32_dpp v244, v112, v220 row_ror:1 row_mask:0xf bank_mask:0xf
	v_fmac_f32_dpp v245, v113, v221 row_ror:1 row_mask:0xf bank_mask:0xf
	v_fmac_f32_dpp v246, v114, v222 row_ror:1 row_mask:0xf bank_mask:0xf
	v_fmac_f32_dpp v247, v115, v223 row_ror:1 row_mask:0xf bank_mask:0xf
	v_fmac_f32_dpp v240, v108, v184 row_shr:2 row_mask:0xf bank_mask:0xf
	v_fmac_f32_dpp v241, v109, v185 row_shr:2 row_mask:0xf bank_mask:0xf
	v_fmac_f32_dpp v242, v110, v186 row_shr:2 row_mask:0xf bank_mask:0xf
	v_fmac_f32_dpp v243, v111, v187 row_shr:2 row_mask:0xf bank_mask:0xf
	v_fmac_f32_dpp v244, v104, v188 row_shr:2 row_mask:0xf bank_mask:0xf
	v_fmac_f32_dpp v245, v105, v189 row_shr:2 row_mask:0xf bank_mask:0xf
	v_fmac_f32_dpp v246, v106, v190 row_shr:2 row_mask:0xf bank_mask:0xf
	v_fmac_f32_dpp v247, v107, v191 row_shr:2 row_mask:0xf bank_mask:0xf
	v_fmac_f32_dpp v240, v116, v224 row_ror:2 row_mask:0xf bank_mask:0xf
	v_fmac_f32_dpp v241, v117, v225 row_ror:2 row_mask:0xf bank_mask:0xf
	v_fmac_f32_dpp v242, v118, v226 row_ror:2 row_mask:0xf bank_mask:0xf
	v_fmac_f32_dpp v243, v119, v227 row_ror:2 row_mask:0xf bank_mask:0xf
	v_fmac_f32_dpp v244, v112, v228 row_ror:2 row_mask:0xf bank_mask:0xf
	v_fmac_f32_dpp v245, v113, v229 row_ror:2 row_mask:0xf bank_mask:0xf
	v_fmac_f32_dpp v246, v114, v230 row_ror:2 row_mask:0xf bank_mask:0xf
	v_fmac_f32_dpp v247, v115, v231 row_ror:2 row_mask:0xf bank_mask:0xf
	v_fmac_f32_dpp v157, v116, v224 row_shr:1 row_mask:0xf bank_mask:0xf
	v_fmac_f32_dpp v157, v117, v225 row_shr:1 row_mask:0xf bank_mask:0xf
	v_fmac_f32_dpp v157, v118, v226 row_shr:1 row_mask:0xf bank_mask:0xf
	v_fmac_f32_dpp v157, v119, v227 row_shr:1 row_mask:0xf bank_mask:0xf
	v_fmac_f32_dpp v157, v112, v228 row_shr:1 row_mask:0xf bank_mask:0xf
	v_fmac_f32_dpp v157, v113, v229 row_shr:1 row_mask:0xf bank_mask:0xf
	v_fmac_f32_dpp v157, v114, v230 row_shr:1 row_mask:0xf bank_mask:0xf
	v_fmac_f32_dpp v157, v115, v231 row_shr:1 row_mask:0xf bank_mask:0xf
	v_fmac_f32_dpp v157, v116, v224 row_shr:1 row_mask:0xf bank_mask:0xf
	v_fmac_f32_dpp v157, v117, v225 row_shr:1 row_mask:0xf bank_mask:0xf
	v_fmac_f32_dpp v157, v118, v226 row_shr:1 row_mask:0xf bank_mask:0xf
	v_fmac_f32_dpp v157, v119, v227 row_shr:1 row_mask:0xf bank_mask:0xf
	v_fmac_f32_dpp v157, v112, v228 row_shr:1 row_mask:0xf bank_mask:0xf
	v_fmac_f32_dpp v157, v113, v229 row_shr:1 row_mask:0xf bank_mask:0xf
	v_fmac_f32_dpp v157, v114, v230 row_shr:1 row_mask:0xf bank_mask:0xf
	v_fmac_f32_dpp v157, v115, v231 row_shr:1 row_mask:0xf bank_mask:0xf
	v_fmac_f32_dpp v157, v116, v224 row_shr:1 row_mask:0xf bank_mask:0xf
	v_fmac_f32_dpp v157, v117, v225 row_shr:1 row_mask:0xf bank_mask:0xf
	v_fmac_f32_dpp v157, v118, v226 row_shr:1 row_mask:0xf bank_mask:0xf
	v_fmac_f32_dpp v157, v119, v227 row_shr:1 row_mask:0xf bank_mask:0xf
	v_fmac_f32_dpp v157, v112, v228 row_shr:1 row_mask:0xf bank_mask:0xf
	v_fmac_f32_dpp v157, v113, v229 row_shr:1 row_mask:0xf bank_mask:0xf
	v_fmac_f32_dpp v157, v114, v230 row_shr:1 row_mask:0xf bank_mask:0xf
	v_fmac_f32_dpp v157, v115, v231 row_shr:1 row_mask:0xf bank_mask:0xf
	v_fmac_f32_dpp v157, v116, v224 row_shr:1 row_mask:0xf bank_mask:0xf
	v_fmac_f32_dpp v157, v117, v225 row_shr:1 row_mask:0xf bank_mask:0xf
	v_fmac_f32_dpp v157, v118, v226 row_shr:1 row_mask:0xf bank_mask:0xf
	v_fmac_f32_dpp v157, v119, v227 row_shr:1 row_mask:0xf bank_mask:0xf
	v_fmac_f32_dpp v157, v112, v228 row_shr:1 row_mask:0xf bank_mask:0xf
	v_fmac_f32_dpp v157, v113, v229 row_shr:1 row_mask:0xf bank_mask:0xf
	v_fmac_f32_dpp v157, v114, v230 row_shr:1 row_mask:0xf bank_mask:0xf
; DEV float bf2f(u16 h) { return __uint_as_float(((uint32_t)h) << 16); }
; DEV void gemm_tile(const u16* __restrict__ A, const u16* __restrict__ Bt, u16* __restrict__ C, int N, int K,
;                    int brow, int bcol, unsigned char* smem, int epi, const GateEpi& ge) {
;     ...
; #pragma unroll
;     for (int ai = 0; ai < 2; ++ai)
; #pragma unroll
;       for (int m = 0; m < 4; ++m) {
;         const int R0 = ai * 128 + wr * 64 + m * 16 + fq2 * 4;
; #pragma unroll
;         for (int n = 0; n < 2; ++n) {
;           const int cl = wc * 32 + n * 16 + fr2, cg = pn * 128 + cl;
;           float am2 = 0.f, am1 = 0.f;
;           if (R0 > 0) { am2 = bf2f(sAt[(R0 - 2) * AS + cl]); am1 = bf2f(sAt[(R0 - 1) * AS + cl]); }
; #pragma unroll
;           for (int j = 0; j < 4; ++j) {
;             const float a0 = acc[ai][0][m][n][j], b0 = acc[ai][1][m][n][j];
;             if (R0 > 0 || j >= 2) {
;               const float gv = gelu_tanh(bs[n] + w0[n] * am2 + w1[n] * am1 + w2[n] * a0) * b0;
;               ge.g[(size_t)(brow + R0 + j) * DFF + cg] = f2bf(gv);
;             } else {
;               ge.first_a[((size_t)pm * 2 + j) * DFF + cg] = sAt[(R0 + j) * AS + cl];
;               ge.first_b[((size_t)pm * 2 + j) * DFF + cg] = f2bf(b0);
;             }
;             if (R0 == 252 && j >= 2) ge.halo_a[((size_t)pm * 2 + (j - 2)) * DFF + cg] = sAt[(R0 + j) * AS + cl];
;             am2 = am1; am1 = a0;
;           }
;         }
;         __builtin_amdgcn_sched_barrier(0);
;       }
	v_fmac_f32_dpp v157, v115, v231 row_shr:1 row_mask:0xf bank_mask:0xf
	v_pk_mul_f32 v[248:249], v[240:241], v[240:241]
	v_pk_mul_f32 v[250:251], v[242:243], v[242:243]
	v_pk_mul_f32 v[182:183], v[244:245], v[244:245]
	v_pk_mul_f32 v[154:155], v[246:247], v[246:247]
	v_pk_fma_f32 v[248:249], v[248:249], s[52:53], v[180:181]
	v_pk_fma_f32 v[250:251], v[250:251], s[52:53], v[180:181]
	v_pk_fma_f32 v[182:183], v[182:183], s[52:53], v[180:181]
	v_pk_fma_f32 v[154:155], v[154:155], s[52:53], v[180:181]
	v_pk_mul_f32 v[248:249], v[240:241], v[248:249]
	v_pk_mul_f32 v[250:251], v[242:243], v[250:251]
	v_pk_mul_f32 v[182:183], v[244:245], v[182:183]
	v_pk_mul_f32 v[154:155], v[246:247], v[154:155]
	v_exp_f32_e32 v248, v248
	v_exp_f32_e32 v249, v249
	v_exp_f32_e32 v250, v250
	v_exp_f32_e32 v251, v251
	v_exp_f32_e32 v182, v182
	v_exp_f32_e32 v183, v183
	v_exp_f32_e32 v154, v154
	v_exp_f32_e32 v155, v155
	v_pk_add_f32 v[248:249], v[248:249], s[94:95]
	v_pk_add_f32 v[250:251], v[250:251], s[94:95]
	v_pk_add_f32 v[182:183], v[182:183], s[94:95]
	v_pk_add_f32 v[154:155], v[154:155], s[94:95]
	v_rcp_f32_e32 v248, v248
	v_rcp_f32_e32 v249, v249
	v_rcp_f32_e32 v250, v250
	v_rcp_f32_e32 v251, v251
	v_rcp_f32_e32 v182, v182
	v_rcp_f32_e32 v183, v183
	v_rcp_f32_e32 v154, v154
	v_rcp_f32_e32 v155, v155
	v_pk_mul_f32 v[240:241], v[240:241], v[248:249]
	v_pk_mul_f32 v[242:243], v[242:243], v[250:251]
	v_pk_mul_f32 v[244:245], v[244:245], v[182:183]
	v_pk_mul_f32 v[246:247], v[246:247], v[154:155]
	v_pk_mul_f32 v[240:241], v[240:241], v[44:45]
	v_pk_mul_f32 v[242:243], v[242:243], v[46:47]
	v_pk_mul_f32 v[244:245], v[244:245], v[40:41]
	v_pk_mul_f32 v[246:247], v[246:247], v[42:43]
	v_cvt_pk_bf16_f32 v248, v240, v241
	v_cvt_pk_bf16_f32 v249, v242, v243
	v_cvt_pk_bf16_f32 v250, v244, v245
	v_cvt_pk_bf16_f32 v251, v246, v247
	global_store_dwordx4 v153, v[248:251], s[0:1]
	s_add_u32 s0, s0, 0x2c000
	s_addc_u32 s1, s1, 0
	v_pk_fma_f32 v[240:241], v[200:201], v[100:101], v[208:209]
	v_pk_fma_f32 v[242:243], v[202:203], v[102:103], v[210:211]
	v_pk_fma_f32 v[244:245], v[204:205], v[96:97], v[212:213]
	v_pk_fma_f32 v[246:247], v[206:207], v[98:99], v[214:215]
	v_fmac_f32_dpp v240, v100, v192 row_shr:1 row_mask:0xf bank_mask:0xf
	v_fmac_f32_dpp v241, v101, v193 row_shr:1 row_mask:0xf bank_mask:0xf
	v_fmac_f32_dpp v242, v102, v194 row_shr:1 row_mask:0xf bank_mask:0xf
	v_fmac_f32_dpp v243, v103, v195 row_shr:1 row_mask:0xf bank_mask:0xf
	v_fmac_f32_dpp v244, v96, v196 row_shr:1 row_mask:0xf bank_mask:0xf
	v_fmac_f32_dpp v245, v97, v197 row_shr:1 row_mask:0xf bank_mask:0xf
	v_fmac_f32_dpp v246, v98, v198 row_shr:1 row_mask:0xf bank_mask:0xf
	v_fmac_f32_dpp v247, v99, v199 row_shr:1 row_mask:0xf bank_mask:0xf
	v_fmac_f32_dpp v240, v108, v216 row_ror:1 row_mask:0xf bank_mask:0xf
	v_fmac_f32_dpp v241, v109, v217 row_ror:1 row_mask:0xf bank_mask:0xf
	v_fmac_f32_dpp v242, v110, v218 row_ror:1 row_mask:0xf bank_mask:0xf
	v_fmac_f32_dpp v243, v111, v219 row_ror:1 row_mask:0xf bank_mask:0xf
	v_fmac_f32_dpp v244, v104, v220 row_ror:1 row_mask:0xf bank_mask:0xf
	v_fmac_f32_dpp v245, v105, v221 row_ror:1 row_mask:0xf bank_mask:0xf
	v_fmac_f32_dpp v246, v106, v222 row_ror:1 row_mask:0xf bank_mask:0xf
	v_fmac_f32_dpp v247, v107, v223 row_ror:1 row_mask:0xf bank_mask:0xf
	v_fmac_f32_dpp v240, v100, v184 row_shr:2 row_mask:0xf bank_mask:0xf
	v_fmac_f32_dpp v241, v101, v185 row_shr:2 row_mask:0xf bank_mask:0xf
	v_fmac_f32_dpp v242, v102, v186 row_shr:2 row_mask:0xf bank_mask:0xf
	v_fmac_f32_dpp v243, v103, v187 row_shr:2 row_mask:0xf bank_mask:0xf
	v_fmac_f32_dpp v244, v96, v188 row_shr:2 row_mask:0xf bank_mask:0xf
	v_fmac_f32_dpp v245, v97, v189 row_shr:2 row_mask:0xf bank_mask:0xf
	v_fmac_f32_dpp v246, v98, v190 row_shr:2 row_mask:0xf bank_mask:0xf
	v_fmac_f32_dpp v247, v99, v191 row_shr:2 row_mask:0xf bank_mask:0xf
	v_fmac_f32_dpp v240, v108, v224 row_ror:2 row_mask:0xf bank_mask:0xf
	v_fmac_f32_dpp v241, v109, v225 row_ror:2 row_mask:0xf bank_mask:0xf
	v_fmac_f32_dpp v242, v110, v226 row_ror:2 row_mask:0xf bank_mask:0xf
	v_fmac_f32_dpp v243, v111, v227 row_ror:2 row_mask:0xf bank_mask:0xf
	v_fmac_f32_dpp v244, v104, v228 row_ror:2 row_mask:0xf bank_mask:0xf
	v_fmac_f32_dpp v245, v105, v229 row_ror:2 row_mask:0xf bank_mask:0xf
	v_fmac_f32_dpp v246, v106, v230 row_ror:2 row_mask:0xf bank_mask:0xf
	v_fmac_f32_dpp v247, v107, v231 row_ror:2 row_mask:0xf bank_mask:0xf
	v_fmac_f32_dpp v157, v108, v224 row_shr:1 row_mask:0xf bank_mask:0xf
	v_fmac_f32_dpp v157, v109, v225 row_shr:1 row_mask:0xf bank_mask:0xf
	v_fmac_f32_dpp v157, v110, v226 row_shr:1 row_mask:0xf bank_mask:0xf
	v_fmac_f32_dpp v157, v111, v227 row_shr:1 row_mask:0xf bank_mask:0xf
	v_fmac_f32_dpp v157, v104, v228 row_shr:1 row_mask:0xf bank_mask:0xf
	v_fmac_f32_dpp v157, v105, v229 row_shr:1 row_mask:0xf bank_mask:0xf
	v_fmac_f32_dpp v157, v106, v230 row_shr:1 row_mask:0xf bank_mask:0xf
	v_fmac_f32_dpp v157, v107, v231 row_shr:1 row_mask:0xf bank_mask:0xf
	v_fmac_f32_dpp v157, v108, v224 row_shr:1 row_mask:0xf bank_mask:0xf
	v_fmac_f32_dpp v157, v109, v225 row_shr:1 row_mask:0xf bank_mask:0xf
	v_fmac_f32_dpp v157, v110, v226 row_shr:1 row_mask:0xf bank_mask:0xf
	v_fmac_f32_dpp v157, v111, v227 row_shr:1 row_mask:0xf bank_mask:0xf
	v_fmac_f32_dpp v157, v104, v228 row_shr:1 row_mask:0xf bank_mask:0xf
	v_fmac_f32_dpp v157, v105, v229 row_shr:1 row_mask:0xf bank_mask:0xf
	v_fmac_f32_dpp v157, v106, v230 row_shr:1 row_mask:0xf bank_mask:0xf
	v_fmac_f32_dpp v157, v107, v231 row_shr:1 row_mask:0xf bank_mask:0xf
	v_fmac_f32_dpp v157, v108, v224 row_shr:1 row_mask:0xf bank_mask:0xf
	v_fmac_f32_dpp v157, v109, v225 row_shr:1 row_mask:0xf bank_mask:0xf
; DEV float bf2f(u16 h) { return __uint_as_float(((uint32_t)h) << 16); }
; DEV void gemm_tile(const u16* __restrict__ A, const u16* __restrict__ Bt, u16* __restrict__ C, int N, int K,
;                    int brow, int bcol, unsigned char* smem, int epi, const GateEpi& ge) {
;     ...
; #pragma unroll
;     for (int ai = 0; ai < 2; ++ai)
; #pragma unroll
;       for (int m = 0; m < 4; ++m) {
;         const int R0 = ai * 128 + wr * 64 + m * 16 + fq2 * 4;
; #pragma unroll
;         for (int n = 0; n < 2; ++n) {
;           const int cl = wc * 32 + n * 16 + fr2, cg = pn * 128 + cl;
;           float am2 = 0.f, am1 = 0.f;
;           if (R0 > 0) { am2 = bf2f(sAt[(R0 - 2) * AS + cl]); am1 = bf2f(sAt[(R0 - 1) * AS + cl]); }
; #pragma unroll
;           for (int j = 0; j < 4; ++j) {
;             const float a0 = acc[ai][0][m][n][j], b0 = acc[ai][1][m][n][j];
;             if (R0 > 0 || j >= 2) {
;               const float gv = gelu_tanh(bs[n] + w0[n] * am2 + w1[n] * am1 + w2[n] * a0) * b0;
;               ge.g[(size_t)(brow + R0 + j) * DFF + cg] = f2bf(gv);
;             } else {
;               ge.first_a[((size_t)pm * 2 + j) * DFF + cg] = sAt[(R0 + j) * AS + cl];
;               ge.first_b[((size_t)pm * 2 + j) * DFF + cg] = f2bf(b0);
;             }
;             if (R0 == 252 && j >= 2) ge.halo_a[((size_t)pm * 2 + (j - 2)) * DFF + cg] = sAt[(R0 + j) * AS + cl];
;             am2 = am1; am1 = a0;
;           }
;         }
;         __builtin_amdgcn_sched_barrier(0);
;       }
	v_fmac_f32_dpp v157, v110, v226 row_shr:1 row_mask:0xf bank_mask:0xf
	v_fmac_f32_dpp v157, v111, v227 row_shr:1 row_mask:0xf bank_mask:0xf
	v_fmac_f32_dpp v157, v104, v228 row_shr:1 row_mask:0xf bank_mask:0xf
	v_fmac_f32_dpp v157, v105, v229 row_shr:1 row_mask:0xf bank_mask:0xf
	v_fmac_f32_dpp v157, v106, v230 row_shr:1 row_mask:0xf bank_mask:0xf
	v_fmac_f32_dpp v157, v107, v231 row_shr:1 row_mask:0xf bank_mask:0xf
	v_fmac_f32_dpp v157, v108, v224 row_shr:1 row_mask:0xf bank_mask:0xf
	v_fmac_f32_dpp v157, v109, v225 row_shr:1 row_mask:0xf bank_mask:0xf
	v_fmac_f32_dpp v157, v110, v226 row_shr:1 row_mask:0xf bank_mask:0xf
	v_fmac_f32_dpp v157, v111, v227 row_shr:1 row_mask:0xf bank_mask:0xf
	v_fmac_f32_dpp v157, v104, v228 row_shr:1 row_mask:0xf bank_mask:0xf
	v_fmac_f32_dpp v157, v105, v229 row_shr:1 row_mask:0xf bank_mask:0xf
	v_fmac_f32_dpp v157, v106, v230 row_shr:1 row_mask:0xf bank_mask:0xf
	v_fmac_f32_dpp v157, v107, v231 row_shr:1 row_mask:0xf bank_mask:0xf
	v_pk_mul_f32 v[248:249], v[240:241], v[240:241]
	v_pk_mul_f32 v[250:251], v[242:243], v[242:243]
	v_pk_mul_f32 v[182:183], v[244:245], v[244:245]
	v_pk_mul_f32 v[154:155], v[246:247], v[246:247]
	v_pk_fma_f32 v[248:249], v[248:249], s[52:53], v[180:181]
	v_pk_fma_f32 v[250:251], v[250:251], s[52:53], v[180:181]
	v_pk_fma_f32 v[182:183], v[182:183], s[52:53], v[180:181]
	v_pk_fma_f32 v[154:155], v[154:155], s[52:53], v[180:181]
	v_pk_mul_f32 v[248:249], v[240:241], v[248:249]
	v_pk_mul_f32 v[250:251], v[242:243], v[250:251]
	v_pk_mul_f32 v[182:183], v[244:245], v[182:183]
	v_pk_mul_f32 v[154:155], v[246:247], v[154:155]
	v_exp_f32_e32 v248, v248
	v_exp_f32_e32 v249, v249
	v_exp_f32_e32 v250, v250
	v_exp_f32_e32 v251, v251
	v_exp_f32_e32 v182, v182
	v_exp_f32_e32 v183, v183
	v_exp_f32_e32 v154, v154
	v_exp_f32_e32 v155, v155
	v_pk_add_f32 v[248:249], v[248:249], s[94:95]
	v_pk_add_f32 v[250:251], v[250:251], s[94:95]
	v_pk_add_f32 v[182:183], v[182:183], s[94:95]
	v_pk_add_f32 v[154:155], v[154:155], s[94:95]
	v_rcp_f32_e32 v248, v248
	v_rcp_f32_e32 v249, v249
	v_rcp_f32_e32 v250, v250
	v_rcp_f32_e32 v251, v251
	v_rcp_f32_e32 v182, v182
	v_rcp_f32_e32 v183, v183
	v_rcp_f32_e32 v154, v154
	v_rcp_f32_e32 v155, v155
	v_pk_mul_f32 v[240:241], v[240:241], v[248:249]
	v_pk_mul_f32 v[242:243], v[242:243], v[250:251]
	v_pk_mul_f32 v[244:245], v[244:245], v[182:183]
	v_pk_mul_f32 v[246:247], v[246:247], v[154:155]
	v_pk_mul_f32 v[240:241], v[240:241], v[36:37]
	v_pk_mul_f32 v[242:243], v[242:243], v[38:39]
	v_pk_mul_f32 v[244:245], v[244:245], v[32:33]
	v_pk_mul_f32 v[246:247], v[246:247], v[34:35]
	v_cvt_pk_bf16_f32 v248, v240, v241
	v_cvt_pk_bf16_f32 v249, v242, v243
	v_cvt_pk_bf16_f32 v250, v244, v245
	v_cvt_pk_bf16_f32 v251, v246, v247
	global_store_dwordx4 v153, v[248:251], s[0:1]
	s_add_u32 s0, s0, 0xdc000
	s_addc_u32 s1, s1, 0
	s_waitcnt lgkmcnt(0)
	v_pk_fma_f32 v[240:241], v[200:201], v[28:29], v[208:209]
	v_pk_fma_f32 v[242:243], v[202:203], v[30:31], v[210:211]
	v_pk_fma_f32 v[244:245], v[204:205], v[24:25], v[212:213]
	v_pk_fma_f32 v[246:247], v[206:207], v[26:27], v[214:215]
	v_fmac_f32_dpp v240, v28, v192 row_shr:1 row_mask:0xf bank_mask:0xf
	v_fmac_f32_dpp v241, v29, v193 row_shr:1 row_mask:0xf bank_mask:0xf
	v_fmac_f32_dpp v242, v30, v194 row_shr:1 row_mask:0xf bank_mask:0xf
	v_fmac_f32_dpp v243, v31, v195 row_shr:1 row_mask:0xf bank_mask:0xf
	v_fmac_f32_dpp v244, v24, v196 row_shr:1 row_mask:0xf bank_mask:0xf
	v_fmac_f32_dpp v245, v25, v197 row_shr:1 row_mask:0xf bank_mask:0xf
	v_fmac_f32_dpp v246, v26, v198 row_shr:1 row_mask:0xf bank_mask:0xf
	v_fmac_f32_dpp v247, v27, v199 row_shr:1 row_mask:0xf bank_mask:0xf
	v_fmac_f32_dpp v240, v232, v216 row_ror:1 row_mask:0xf bank_mask:0xf
	v_fmac_f32_dpp v241, v233, v217 row_ror:1 row_mask:0xf bank_mask:0xf
	v_fmac_f32_dpp v242, v234, v218 row_ror:1 row_mask:0xf bank_mask:0xf
	v_fmac_f32_dpp v243, v235, v219 row_ror:1 row_mask:0xf bank_mask:0xf
	v_fmac_f32_dpp v244, v236, v220 row_ror:1 row_mask:0xf bank_mask:0xf
	v_fmac_f32_dpp v245, v237, v221 row_ror:1 row_mask:0xf bank_mask:0xf
	v_fmac_f32_dpp v246, v238, v222 row_ror:1 row_mask:0xf bank_mask:0xf
	v_fmac_f32_dpp v247, v239, v223 row_ror:1 row_mask:0xf bank_mask:0xf
	v_fmac_f32_dpp v240, v28, v184 row_shr:2 row_mask:0xf bank_mask:0xf
	v_fmac_f32_dpp v241, v29, v185 row_shr:2 row_mask:0xf bank_mask:0xf
	v_fmac_f32_dpp v242, v30, v186 row_shr:2 row_mask:0xf bank_mask:0xf
	v_fmac_f32_dpp v243, v31, v187 row_shr:2 row_mask:0xf bank_mask:0xf
	v_fmac_f32_dpp v244, v24, v188 row_shr:2 row_mask:0xf bank_mask:0xf
	v_fmac_f32_dpp v245, v25, v189 row_shr:2 row_mask:0xf bank_mask:0xf
	v_fmac_f32_dpp v246, v26, v190 row_shr:2 row_mask:0xf bank_mask:0xf
	v_fmac_f32_dpp v247, v27, v191 row_shr:2 row_mask:0xf bank_mask:0xf
	v_fmac_f32_dpp v240, v232, v224 row_ror:2 row_mask:0xf bank_mask:0xf
	v_fmac_f32_dpp v241, v233, v225 row_ror:2 row_mask:0xf bank_mask:0xf
	v_fmac_f32_dpp v242, v234, v226 row_ror:2 row_mask:0xf bank_mask:0xf
	v_fmac_f32_dpp v243, v235, v227 row_ror:2 row_mask:0xf bank_mask:0xf
	v_fmac_f32_dpp v244, v236, v228 row_ror:2 row_mask:0xf bank_mask:0xf
	v_fmac_f32_dpp v245, v237, v229 row_ror:2 row_mask:0xf bank_mask:0xf
	v_fmac_f32_dpp v246, v238, v230 row_ror:2 row_mask:0xf bank_mask:0xf
	v_fmac_f32_dpp v247, v239, v231 row_ror:2 row_mask:0xf bank_mask:0xf
	v_fmac_f32_dpp v157, v232, v224 row_shr:1 row_mask:0xf bank_mask:0xf
	v_fmac_f32_dpp v157, v233, v225 row_shr:1 row_mask:0xf bank_mask:0xf
	v_fmac_f32_dpp v157, v234, v226 row_shr:1 row_mask:0xf bank_mask:0xf
	v_fmac_f32_dpp v157, v235, v227 row_shr:1 row_mask:0xf bank_mask:0xf
	v_fmac_f32_dpp v157, v236, v228 row_shr:1 row_mask:0xf bank_mask:0xf
; DEV float bf2f(u16 h) { return __uint_as_float(((uint32_t)h) << 16); }
; DEV void gemm_tile(const u16* __restrict__ A, const u16* __restrict__ Bt, u16* __restrict__ C, int N, int K,
;                    int brow, int bcol, unsigned char* smem, int epi, const GateEpi& ge) {
;     ...
; #pragma unroll
;     for (int ai = 0; ai < 2; ++ai)
; #pragma unroll
;       for (int m = 0; m < 4; ++m) {
;         const int R0 = ai * 128 + wr * 64 + m * 16 + fq2 * 4;
; #pragma unroll
;         for (int n = 0; n < 2; ++n) {
;           const int cl = wc * 32 + n * 16 + fr2, cg = pn * 128 + cl;
;           float am2 = 0.f, am1 = 0.f;
;           if (R0 > 0) { am2 = bf2f(sAt[(R0 - 2) * AS + cl]); am1 = bf2f(sAt[(R0 - 1) * AS + cl]); }
; #pragma unroll
;           for (int j = 0; j < 4; ++j) {
;             const float a0 = acc[ai][0][m][n][j], b0 = acc[ai][1][m][n][j];
;             if (R0 > 0 || j >= 2) {
;               const float gv = gelu_tanh(bs[n] + w0[n] * am2 + w1[n] * am1 + w2[n] * a0) * b0;
;               ge.g[(size_t)(brow + R0 + j) * DFF + cg] = f2bf(gv);
;             } else {
;               ge.first_a[((size_t)pm * 2 + j) * DFF + cg] = sAt[(R0 + j) * AS + cl];
;               ge.first_b[((size_t)pm * 2 + j) * DFF + cg] = f2bf(b0);
;             }
;             if (R0 == 252 && j >= 2) ge.halo_a[((size_t)pm * 2 + (j - 2)) * DFF + cg] = sAt[(R0 + j) * AS + cl];
;             am2 = am1; am1 = a0;
;           }
;         }
;         __builtin_amdgcn_sched_barrier(0);
;       }
	v_fmac_f32_dpp v157, v237, v229 row_shr:1 row_mask:0xf bank_mask:0xf
	v_fmac_f32_dpp v157, v238, v230 row_shr:1 row_mask:0xf bank_mask:0xf
	v_fmac_f32_dpp v157, v239, v231 row_shr:1 row_mask:0xf bank_mask:0xf
	v_fmac_f32_dpp v157, v232, v224 row_shr:1 row_mask:0xf bank_mask:0xf
	v_fmac_f32_dpp v157, v233, v225 row_shr:1 row_mask:0xf bank_mask:0xf
	v_fmac_f32_dpp v157, v234, v226 row_shr:1 row_mask:0xf bank_mask:0xf
	v_fmac_f32_dpp v157, v235, v227 row_shr:1 row_mask:0xf bank_mask:0xf
	v_fmac_f32_dpp v157, v236, v228 row_shr:1 row_mask:0xf bank_mask:0xf
	v_fmac_f32_dpp v157, v237, v229 row_shr:1 row_mask:0xf bank_mask:0xf
	v_fmac_f32_dpp v157, v238, v230 row_shr:1 row_mask:0xf bank_mask:0xf
	v_fmac_f32_dpp v157, v239, v231 row_shr:1 row_mask:0xf bank_mask:0xf
	v_fmac_f32_dpp v157, v232, v224 row_shr:1 row_mask:0xf bank_mask:0xf
	v_fmac_f32_dpp v157, v233, v225 row_shr:1 row_mask:0xf bank_mask:0xf
	v_fmac_f32_dpp v157, v234, v226 row_shr:1 row_mask:0xf bank_mask:0xf
	v_fmac_f32_dpp v157, v235, v227 row_shr:1 row_mask:0xf bank_mask:0xf
	v_fmac_f32_dpp v157, v236, v228 row_shr:1 row_mask:0xf bank_mask:0xf
	v_fmac_f32_dpp v157, v237, v229 row_shr:1 row_mask:0xf bank_mask:0xf
	v_fmac_f32_dpp v157, v238, v230 row_shr:1 row_mask:0xf bank_mask:0xf
	v_fmac_f32_dpp v157, v239, v231 row_shr:1 row_mask:0xf bank_mask:0xf
	v_fmac_f32_dpp v157, v232, v224 row_shr:1 row_mask:0xf bank_mask:0xf
	v_fmac_f32_dpp v157, v233, v225 row_shr:1 row_mask:0xf bank_mask:0xf
	v_fmac_f32_dpp v157, v234, v226 row_shr:1 row_mask:0xf bank_mask:0xf
	v_fmac_f32_dpp v157, v235, v227 row_shr:1 row_mask:0xf bank_mask:0xf
	v_fmac_f32_dpp v157, v236, v228 row_shr:1 row_mask:0xf bank_mask:0xf
	v_fmac_f32_dpp v157, v237, v229 row_shr:1 row_mask:0xf bank_mask:0xf
	v_fmac_f32_dpp v157, v238, v230 row_shr:1 row_mask:0xf bank_mask:0xf
	v_fmac_f32_dpp v157, v239, v231 row_shr:1 row_mask:0xf bank_mask:0xf
	v_pk_mul_f32 v[248:249], v[240:241], v[240:241]
	v_pk_mul_f32 v[250:251], v[242:243], v[242:243]
	v_pk_mul_f32 v[182:183], v[244:245], v[244:245]
	v_pk_mul_f32 v[154:155], v[246:247], v[246:247]
	v_pk_fma_f32 v[248:249], v[248:249], s[52:53], v[180:181]
	v_pk_fma_f32 v[250:251], v[250:251], s[52:53], v[180:181]
	v_pk_fma_f32 v[182:183], v[182:183], s[52:53], v[180:181]
	v_pk_fma_f32 v[154:155], v[154:155], s[52:53], v[180:181]
	v_pk_mul_f32 v[248:249], v[240:241], v[248:249]
	v_pk_mul_f32 v[250:251], v[242:243], v[250:251]
	v_pk_mul_f32 v[182:183], v[244:245], v[182:183]
	v_pk_mul_f32 v[154:155], v[246:247], v[154:155]
	v_exp_f32_e32 v248, v248
	v_exp_f32_e32 v249, v249
	v_exp_f32_e32 v250, v250
	v_exp_f32_e32 v251, v251
	v_exp_f32_e32 v182, v182
	v_exp_f32_e32 v183, v183
	v_exp_f32_e32 v154, v154
	v_exp_f32_e32 v155, v155
	v_pk_add_f32 v[248:249], v[248:249], s[94:95]
	v_pk_add_f32 v[250:251], v[250:251], s[94:95]
	v_pk_add_f32 v[182:183], v[182:183], s[94:95]
	v_pk_add_f32 v[154:155], v[154:155], s[94:95]
	v_rcp_f32_e32 v248, v248
	v_rcp_f32_e32 v249, v249
	v_rcp_f32_e32 v250, v250
	v_rcp_f32_e32 v251, v251
	v_rcp_f32_e32 v182, v182
	v_rcp_f32_e32 v183, v183
	v_rcp_f32_e32 v154, v154
	v_rcp_f32_e32 v155, v155
	v_pk_mul_f32 v[240:241], v[240:241], v[248:249]
	v_pk_mul_f32 v[242:243], v[242:243], v[250:251]
	v_pk_mul_f32 v[244:245], v[244:245], v[182:183]
	v_pk_mul_f32 v[246:247], v[246:247], v[154:155]
	v_pk_mul_f32 v[240:241], v[240:241], v[56:57]
	v_pk_mul_f32 v[242:243], v[242:243], v[58:59]
	v_pk_mul_f32 v[244:245], v[244:245], v[60:61]
	v_pk_mul_f32 v[246:247], v[246:247], v[62:63]
	v_cvt_pk_bf16_f32 v248, v240, v241
	v_cvt_pk_bf16_f32 v249, v242, v243
	v_cvt_pk_bf16_f32 v250, v244, v245
	v_cvt_pk_bf16_f32 v251, v246, v247
	global_store_dwordx4 v153, v[248:251], s[0:1]
	s_add_u32 s0, s0, 0x2c000
	s_addc_u32 s1, s1, 0
	v_pk_fma_f32 v[240:241], v[200:201], v[20:21], v[208:209]
	v_pk_fma_f32 v[242:243], v[202:203], v[22:23], v[210:211]
	v_pk_fma_f32 v[244:245], v[204:205], v[16:17], v[212:213]
	v_pk_fma_f32 v[246:247], v[206:207], v[18:19], v[214:215]
	v_fmac_f32_dpp v240, v20, v192 row_shr:1 row_mask:0xf bank_mask:0xf
	v_fmac_f32_dpp v241, v21, v193 row_shr:1 row_mask:0xf bank_mask:0xf
	v_fmac_f32_dpp v242, v22, v194 row_shr:1 row_mask:0xf bank_mask:0xf
	v_fmac_f32_dpp v243, v23, v195 row_shr:1 row_mask:0xf bank_mask:0xf
	v_fmac_f32_dpp v244, v16, v196 row_shr:1 row_mask:0xf bank_mask:0xf
	v_fmac_f32_dpp v245, v17, v197 row_shr:1 row_mask:0xf bank_mask:0xf
	v_fmac_f32_dpp v246, v18, v198 row_shr:1 row_mask:0xf bank_mask:0xf
	v_fmac_f32_dpp v247, v19, v199 row_shr:1 row_mask:0xf bank_mask:0xf
	v_fmac_f32_dpp v240, v28, v216 row_ror:1 row_mask:0xf bank_mask:0xf
	v_fmac_f32_dpp v241, v29, v217 row_ror:1 row_mask:0xf bank_mask:0xf
	v_fmac_f32_dpp v242, v30, v218 row_ror:1 row_mask:0xf bank_mask:0xf
	v_fmac_f32_dpp v243, v31, v219 row_ror:1 row_mask:0xf bank_mask:0xf
	v_fmac_f32_dpp v244, v24, v220 row_ror:1 row_mask:0xf bank_mask:0xf
	v_fmac_f32_dpp v245, v25, v221 row_ror:1 row_mask:0xf bank_mask:0xf
	v_fmac_f32_dpp v246, v26, v222 row_ror:1 row_mask:0xf bank_mask:0xf
	v_fmac_f32_dpp v247, v27, v223 row_ror:1 row_mask:0xf bank_mask:0xf
	v_fmac_f32_dpp v240, v20, v184 row_shr:2 row_mask:0xf bank_mask:0xf
	v_fmac_f32_dpp v241, v21, v185 row_shr:2 row_mask:0xf bank_mask:0xf
	v_fmac_f32_dpp v242, v22, v186 row_shr:2 row_mask:0xf bank_mask:0xf
	v_fmac_f32_dpp v243, v23, v187 row_shr:2 row_mask:0xf bank_mask:0xf
	v_fmac_f32_dpp v244, v16, v188 row_shr:2 row_mask:0xf bank_mask:0xf
	v_fmac_f32_dpp v245, v17, v189 row_shr:2 row_mask:0xf bank_mask:0xf
	v_fmac_f32_dpp v246, v18, v190 row_shr:2 row_mask:0xf bank_mask:0xf
	v_fmac_f32_dpp v247, v19, v191 row_shr:2 row_mask:0xf bank_mask:0xf
; DEV float bf2f(u16 h) { return __uint_as_float(((uint32_t)h) << 16); }
; DEV void gemm_tile(const u16* __restrict__ A, const u16* __restrict__ Bt, u16* __restrict__ C, int N, int K,
;                    int brow, int bcol, unsigned char* smem, int epi, const GateEpi& ge) {
;     ...
; #pragma unroll
;     for (int ai = 0; ai < 2; ++ai)
; #pragma unroll
;       for (int m = 0; m < 4; ++m) {
;         const int R0 = ai * 128 + wr * 64 + m * 16 + fq2 * 4;
; #pragma unroll
;         for (int n = 0; n < 2; ++n) {
;           const int cl = wc * 32 + n * 16 + fr2, cg = pn * 128 + cl;
;           float am2 = 0.f, am1 = 0.f;
;           if (R0 > 0) { am2 = bf2f(sAt[(R0 - 2) * AS + cl]); am1 = bf2f(sAt[(R0 - 1) * AS + cl]); }
; #pragma unroll
;           for (int j = 0; j < 4; ++j) {
;             const float a0 = acc[ai][0][m][n][j], b0 = acc[ai][1][m][n][j];
;             if (R0 > 0 || j >= 2) {
;               const float gv = gelu_tanh(bs[n] + w0[n] * am2 + w1[n] * am1 + w2[n] * a0) * b0;
;               ge.g[(size_t)(brow + R0 + j) * DFF + cg] = f2bf(gv);
;             } else {
;               ge.first_a[((size_t)pm * 2 + j) * DFF + cg] = sAt[(R0 + j) * AS + cl];
;               ge.first_b[((size_t)pm * 2 + j) * DFF + cg] = f2bf(b0);
;             }
;             if (R0 == 252 && j >= 2) ge.halo_a[((size_t)pm * 2 + (j - 2)) * DFF + cg] = sAt[(R0 + j) * AS + cl];
;             am2 = am1; am1 = a0;
;           }
;         }
;         __builtin_amdgcn_sched_barrier(0);
;       }
	v_fmac_f32_dpp v240, v28, v224 row_ror:2 row_mask:0xf bank_mask:0xf
	v_fmac_f32_dpp v241, v29, v225 row_ror:2 row_mask:0xf bank_mask:0xf
	v_fmac_f32_dpp v242, v30, v226 row_ror:2 row_mask:0xf bank_mask:0xf
	v_fmac_f32_dpp v243, v31, v227 row_ror:2 row_mask:0xf bank_mask:0xf
	v_fmac_f32_dpp v244, v24, v228 row_ror:2 row_mask:0xf bank_mask:0xf
	v_fmac_f32_dpp v245, v25, v229 row_ror:2 row_mask:0xf bank_mask:0xf
	v_fmac_f32_dpp v246, v26, v230 row_ror:2 row_mask:0xf bank_mask:0xf
	v_fmac_f32_dpp v247, v27, v231 row_ror:2 row_mask:0xf bank_mask:0xf
	v_fmac_f32_dpp v157, v28, v224 row_shr:1 row_mask:0xf bank_mask:0xf
	v_fmac_f32_dpp v157, v29, v225 row_shr:1 row_mask:0xf bank_mask:0xf
	v_fmac_f32_dpp v157, v30, v226 row_shr:1 row_mask:0xf bank_mask:0xf
	v_fmac_f32_dpp v157, v31, v227 row_shr:1 row_mask:0xf bank_mask:0xf
	v_fmac_f32_dpp v157, v24, v228 row_shr:1 row_mask:0xf bank_mask:0xf
	v_fmac_f32_dpp v157, v25, v229 row_shr:1 row_mask:0xf bank_mask:0xf
	v_fmac_f32_dpp v157, v26, v230 row_shr:1 row_mask:0xf bank_mask:0xf
	v_fmac_f32_dpp v157, v27, v231 row_shr:1 row_mask:0xf bank_mask:0xf
	v_fmac_f32_dpp v157, v28, v224 row_shr:1 row_mask:0xf bank_mask:0xf
	v_fmac_f32_dpp v157, v29, v225 row_shr:1 row_mask:0xf bank_mask:0xf
	v_fmac_f32_dpp v157, v30, v226 row_shr:1 row_mask:0xf bank_mask:0xf
	v_fmac_f32_dpp v157, v31, v227 row_shr:1 row_mask:0xf bank_mask:0xf
	v_fmac_f32_dpp v157, v24, v228 row_shr:1 row_mask:0xf bank_mask:0xf
	v_fmac_f32_dpp v157, v25, v229 row_shr:1 row_mask:0xf bank_mask:0xf
	v_fmac_f32_dpp v157, v26, v230 row_shr:1 row_mask:0xf bank_mask:0xf
	v_fmac_f32_dpp v157, v27, v231 row_shr:1 row_mask:0xf bank_mask:0xf
	v_fmac_f32_dpp v157, v28, v224 row_shr:1 row_mask:0xf bank_mask:0xf
	v_fmac_f32_dpp v157, v29, v225 row_shr:1 row_mask:0xf bank_mask:0xf
	v_fmac_f32_dpp v157, v30, v226 row_shr:1 row_mask:0xf bank_mask:0xf
	v_fmac_f32_dpp v157, v31, v227 row_shr:1 row_mask:0xf bank_mask:0xf
	v_fmac_f32_dpp v157, v24, v228 row_shr:1 row_mask:0xf bank_mask:0xf
	v_fmac_f32_dpp v157, v25, v229 row_shr:1 row_mask:0xf bank_mask:0xf
	v_fmac_f32_dpp v157, v26, v230 row_shr:1 row_mask:0xf bank_mask:0xf
	v_fmac_f32_dpp v157, v27, v231 row_shr:1 row_mask:0xf bank_mask:0xf
	v_fmac_f32_dpp v157, v28, v224 row_shr:1 row_mask:0xf bank_mask:0xf
	v_fmac_f32_dpp v157, v29, v225 row_shr:1 row_mask:0xf bank_mask:0xf
	v_fmac_f32_dpp v157, v30, v226 row_shr:1 row_mask:0xf bank_mask:0xf
	v_fmac_f32_dpp v157, v31, v227 row_shr:1 row_mask:0xf bank_mask:0xf
	v_fmac_f32_dpp v157, v24, v228 row_shr:1 row_mask:0xf bank_mask:0xf
	v_fmac_f32_dpp v157, v25, v229 row_shr:1 row_mask:0xf bank_mask:0xf
	v_fmac_f32_dpp v157, v26, v230 row_shr:1 row_mask:0xf bank_mask:0xf
	v_fmac_f32_dpp v157, v27, v231 row_shr:1 row_mask:0xf bank_mask:0xf
	v_pk_mul_f32 v[248:249], v[240:241], v[240:241]
	v_pk_mul_f32 v[250:251], v[242:243], v[242:243]
	v_pk_mul_f32 v[182:183], v[244:245], v[244:245]
	v_pk_mul_f32 v[154:155], v[246:247], v[246:247]
	v_pk_fma_f32 v[248:249], v[248:249], s[52:53], v[180:181]
	v_pk_fma_f32 v[250:251], v[250:251], s[52:53], v[180:181]
	v_pk_fma_f32 v[182:183], v[182:183], s[52:53], v[180:181]
	v_pk_fma_f32 v[154:155], v[154:155], s[52:53], v[180:181]
	v_pk_mul_f32 v[248:249], v[240:241], v[248:249]
	v_pk_mul_f32 v[250:251], v[242:243], v[250:251]
	v_pk_mul_f32 v[182:183], v[244:245], v[182:183]
	v_pk_mul_f32 v[154:155], v[246:247], v[154:155]
	v_exp_f32_e32 v248, v248
	v_exp_f32_e32 v249, v249
	v_exp_f32_e32 v250, v250
	v_exp_f32_e32 v251, v251
	v_exp_f32_e32 v182, v182
	v_exp_f32_e32 v183, v183
	v_exp_f32_e32 v154, v154
	v_exp_f32_e32 v155, v155
	v_pk_add_f32 v[248:249], v[248:249], s[94:95]
	v_pk_add_f32 v[250:251], v[250:251], s[94:95]
	v_pk_add_f32 v[182:183], v[182:183], s[94:95]
	v_pk_add_f32 v[154:155], v[154:155], s[94:95]
	v_rcp_f32_e32 v248, v248
	v_rcp_f32_e32 v249, v249
	v_rcp_f32_e32 v250, v250
	v_rcp_f32_e32 v251, v251
	v_rcp_f32_e32 v182, v182
	v_rcp_f32_e32 v183, v183
	v_rcp_f32_e32 v154, v154
	v_rcp_f32_e32 v155, v155
	v_pk_mul_f32 v[240:241], v[240:241], v[248:249]
	v_pk_mul_f32 v[242:243], v[242:243], v[250:251]
	v_pk_mul_f32 v[244:245], v[244:245], v[182:183]
	v_pk_mul_f32 v[246:247], v[246:247], v[154:155]
	v_pk_mul_f32 v[240:241], v[240:241], v[64:65]
	v_pk_mul_f32 v[242:243], v[242:243], v[66:67]
	v_pk_mul_f32 v[244:245], v[244:245], v[72:73]
	v_pk_mul_f32 v[246:247], v[246:247], v[74:75]
	v_cvt_pk_bf16_f32 v248, v240, v241
	v_cvt_pk_bf16_f32 v249, v242, v243
	v_cvt_pk_bf16_f32 v250, v244, v245
	v_cvt_pk_bf16_f32 v251, v246, v247
	global_store_dwordx4 v153, v[248:251], s[0:1]
	s_add_u32 s0, s0, 0x2c000
	s_addc_u32 s1, s1, 0
	v_pk_fma_f32 v[240:241], v[200:201], v[12:13], v[208:209]
	v_pk_fma_f32 v[242:243], v[202:203], v[14:15], v[210:211]
	v_pk_fma_f32 v[244:245], v[204:205], v[8:9], v[212:213]
	v_pk_fma_f32 v[246:247], v[206:207], v[10:11], v[214:215]
	v_fmac_f32_dpp v240, v12, v192 row_shr:1 row_mask:0xf bank_mask:0xf
	v_fmac_f32_dpp v241, v13, v193 row_shr:1 row_mask:0xf bank_mask:0xf
	v_fmac_f32_dpp v242, v14, v194 row_shr:1 row_mask:0xf bank_mask:0xf
	v_fmac_f32_dpp v243, v15, v195 row_shr:1 row_mask:0xf bank_mask:0xf
	v_fmac_f32_dpp v244, v8, v196 row_shr:1 row_mask:0xf bank_mask:0xf
	v_fmac_f32_dpp v245, v9, v197 row_shr:1 row_mask:0xf bank_mask:0xf
	v_fmac_f32_dpp v246, v10, v198 row_shr:1 row_mask:0xf bank_mask:0xf
	v_fmac_f32_dpp v247, v11, v199 row_shr:1 row_mask:0xf bank_mask:0xf
	v_fmac_f32_dpp v240, v20, v216 row_ror:1 row_mask:0xf bank_mask:0xf
	v_fmac_f32_dpp v241, v21, v217 row_ror:1 row_mask:0xf bank_mask:0xf
	v_fmac_f32_dpp v242, v22, v218 row_ror:1 row_mask:0xf bank_mask:0xf
; DEV float bf2f(u16 h) { return __uint_as_float(((uint32_t)h) << 16); }
; DEV void gemm_tile(const u16* __restrict__ A, const u16* __restrict__ Bt, u16* __restrict__ C, int N, int K,
;                    int brow, int bcol, unsigned char* smem, int epi, const GateEpi& ge) {
;     ...
; #pragma unroll
;     for (int ai = 0; ai < 2; ++ai)
; #pragma unroll
;       for (int m = 0; m < 4; ++m) {
;         const int R0 = ai * 128 + wr * 64 + m * 16 + fq2 * 4;
; #pragma unroll
;         for (int n = 0; n < 2; ++n) {
;           const int cl = wc * 32 + n * 16 + fr2, cg = pn * 128 + cl;
;           float am2 = 0.f, am1 = 0.f;
;           if (R0 > 0) { am2 = bf2f(sAt[(R0 - 2) * AS + cl]); am1 = bf2f(sAt[(R0 - 1) * AS + cl]); }
; #pragma unroll
;           for (int j = 0; j < 4; ++j) {
;             const float a0 = acc[ai][0][m][n][j], b0 = acc[ai][1][m][n][j];
;             if (R0 > 0 || j >= 2) {
;               const float gv = gelu_tanh(bs[n] + w0[n] * am2 + w1[n] * am1 + w2[n] * a0) * b0;
;               ge.g[(size_t)(brow + R0 + j) * DFF + cg] = f2bf(gv);
;             } else {
;               ge.first_a[((size_t)pm * 2 + j) * DFF + cg] = sAt[(R0 + j) * AS + cl];
;               ge.first_b[((size_t)pm * 2 + j) * DFF + cg] = f2bf(b0);
;             }
;             if (R0 == 252 && j >= 2) ge.halo_a[((size_t)pm * 2 + (j - 2)) * DFF + cg] = sAt[(R0 + j) * AS + cl];
;             am2 = am1; am1 = a0;
;           }
;         }
;         __builtin_amdgcn_sched_barrier(0);
;       }
	v_fmac_f32_dpp v243, v23, v219 row_ror:1 row_mask:0xf bank_mask:0xf
	v_fmac_f32_dpp v244, v16, v220 row_ror:1 row_mask:0xf bank_mask:0xf
	v_fmac_f32_dpp v245, v17, v221 row_ror:1 row_mask:0xf bank_mask:0xf
	v_fmac_f32_dpp v246, v18, v222 row_ror:1 row_mask:0xf bank_mask:0xf
	v_fmac_f32_dpp v247, v19, v223 row_ror:1 row_mask:0xf bank_mask:0xf
	v_fmac_f32_dpp v240, v12, v184 row_shr:2 row_mask:0xf bank_mask:0xf
	v_fmac_f32_dpp v241, v13, v185 row_shr:2 row_mask:0xf bank_mask:0xf
	v_fmac_f32_dpp v242, v14, v186 row_shr:2 row_mask:0xf bank_mask:0xf
	v_fmac_f32_dpp v243, v15, v187 row_shr:2 row_mask:0xf bank_mask:0xf
	v_fmac_f32_dpp v244, v8, v188 row_shr:2 row_mask:0xf bank_mask:0xf
	v_fmac_f32_dpp v245, v9, v189 row_shr:2 row_mask:0xf bank_mask:0xf
	v_fmac_f32_dpp v246, v10, v190 row_shr:2 row_mask:0xf bank_mask:0xf
	v_fmac_f32_dpp v247, v11, v191 row_shr:2 row_mask:0xf bank_mask:0xf
	v_fmac_f32_dpp v240, v20, v224 row_ror:2 row_mask:0xf bank_mask:0xf
	v_fmac_f32_dpp v241, v21, v225 row_ror:2 row_mask:0xf bank_mask:0xf
	v_fmac_f32_dpp v242, v22, v226 row_ror:2 row_mask:0xf bank_mask:0xf
	v_fmac_f32_dpp v243, v23, v227 row_ror:2 row_mask:0xf bank_mask:0xf
	v_fmac_f32_dpp v244, v16, v228 row_ror:2 row_mask:0xf bank_mask:0xf
	v_fmac_f32_dpp v245, v17, v229 row_ror:2 row_mask:0xf bank_mask:0xf
	v_fmac_f32_dpp v246, v18, v230 row_ror:2 row_mask:0xf bank_mask:0xf
	v_fmac_f32_dpp v247, v19, v231 row_ror:2 row_mask:0xf bank_mask:0xf
	v_fmac_f32_dpp v157, v20, v224 row_shr:1 row_mask:0xf bank_mask:0xf
	v_fmac_f32_dpp v157, v21, v225 row_shr:1 row_mask:0xf bank_mask:0xf
	v_fmac_f32_dpp v157, v22, v226 row_shr:1 row_mask:0xf bank_mask:0xf
	v_fmac_f32_dpp v157, v23, v227 row_shr:1 row_mask:0xf bank_mask:0xf
	v_fmac_f32_dpp v157, v16, v228 row_shr:1 row_mask:0xf bank_mask:0xf
	v_fmac_f32_dpp v157, v17, v229 row_shr:1 row_mask:0xf bank_mask:0xf
	v_fmac_f32_dpp v157, v18, v230 row_shr:1 row_mask:0xf bank_mask:0xf
	v_fmac_f32_dpp v157, v19, v231 row_shr:1 row_mask:0xf bank_mask:0xf
	v_fmac_f32_dpp v157, v20, v224 row_shr:1 row_mask:0xf bank_mask:0xf
	v_fmac_f32_dpp v157, v21, v225 row_shr:1 row_mask:0xf bank_mask:0xf
	v_fmac_f32_dpp v157, v22, v226 row_shr:1 row_mask:0xf bank_mask:0xf
	v_fmac_f32_dpp v157, v23, v227 row_shr:1 row_mask:0xf bank_mask:0xf
	v_fmac_f32_dpp v157, v16, v228 row_shr:1 row_mask:0xf bank_mask:0xf
	v_fmac_f32_dpp v157, v17, v229 row_shr:1 row_mask:0xf bank_mask:0xf
	v_fmac_f32_dpp v157, v18, v230 row_shr:1 row_mask:0xf bank_mask:0xf
	v_fmac_f32_dpp v157, v19, v231 row_shr:1 row_mask:0xf bank_mask:0xf
	v_fmac_f32_dpp v157, v20, v224 row_shr:1 row_mask:0xf bank_mask:0xf
	v_fmac_f32_dpp v157, v21, v225 row_shr:1 row_mask:0xf bank_mask:0xf
	v_fmac_f32_dpp v157, v22, v226 row_shr:1 row_mask:0xf bank_mask:0xf
	v_fmac_f32_dpp v157, v23, v227 row_shr:1 row_mask:0xf bank_mask:0xf
	v_fmac_f32_dpp v157, v16, v228 row_shr:1 row_mask:0xf bank_mask:0xf
	v_fmac_f32_dpp v157, v17, v229 row_shr:1 row_mask:0xf bank_mask:0xf
	v_fmac_f32_dpp v157, v18, v230 row_shr:1 row_mask:0xf bank_mask:0xf
	v_fmac_f32_dpp v157, v19, v231 row_shr:1 row_mask:0xf bank_mask:0xf
	v_fmac_f32_dpp v157, v20, v224 row_shr:1 row_mask:0xf bank_mask:0xf
	v_fmac_f32_dpp v157, v21, v225 row_shr:1 row_mask:0xf bank_mask:0xf
	v_fmac_f32_dpp v157, v22, v226 row_shr:1 row_mask:0xf bank_mask:0xf
	v_fmac_f32_dpp v157, v23, v227 row_shr:1 row_mask:0xf bank_mask:0xf
	v_fmac_f32_dpp v157, v16, v228 row_shr:1 row_mask:0xf bank_mask:0xf
	v_fmac_f32_dpp v157, v17, v229 row_shr:1 row_mask:0xf bank_mask:0xf
	v_fmac_f32_dpp v157, v18, v230 row_shr:1 row_mask:0xf bank_mask:0xf
	v_fmac_f32_dpp v157, v19, v231 row_shr:1 row_mask:0xf bank_mask:0xf
	v_pk_mul_f32 v[248:249], v[240:241], v[240:241]
	v_pk_mul_f32 v[250:251], v[242:243], v[242:243]
	v_pk_mul_f32 v[182:183], v[244:245], v[244:245]
	v_pk_mul_f32 v[154:155], v[246:247], v[246:247]
	v_pk_fma_f32 v[248:249], v[248:249], s[52:53], v[180:181]
	v_pk_fma_f32 v[250:251], v[250:251], s[52:53], v[180:181]
	v_pk_fma_f32 v[182:183], v[182:183], s[52:53], v[180:181]
	v_pk_fma_f32 v[154:155], v[154:155], s[52:53], v[180:181]
	v_pk_mul_f32 v[248:249], v[240:241], v[248:249]
	v_pk_mul_f32 v[250:251], v[242:243], v[250:251]
	v_pk_mul_f32 v[182:183], v[244:245], v[182:183]
	v_pk_mul_f32 v[154:155], v[246:247], v[154:155]
	v_exp_f32_e32 v248, v248
	v_exp_f32_e32 v249, v249
	v_exp_f32_e32 v250, v250
	v_exp_f32_e32 v251, v251
	v_exp_f32_e32 v182, v182
	v_exp_f32_e32 v183, v183
	v_exp_f32_e32 v154, v154
	v_exp_f32_e32 v155, v155
	v_pk_add_f32 v[248:249], v[248:249], s[94:95]
	v_pk_add_f32 v[250:251], v[250:251], s[94:95]
	v_pk_add_f32 v[182:183], v[182:183], s[94:95]
	v_pk_add_f32 v[154:155], v[154:155], s[94:95]
	v_rcp_f32_e32 v248, v248
	v_rcp_f32_e32 v249, v249
	v_rcp_f32_e32 v250, v250
	v_rcp_f32_e32 v251, v251
	v_rcp_f32_e32 v182, v182
	v_rcp_f32_e32 v183, v183
	v_rcp_f32_e32 v154, v154
	v_rcp_f32_e32 v155, v155
	v_pk_mul_f32 v[240:241], v[240:241], v[248:249]
	v_pk_mul_f32 v[242:243], v[242:243], v[250:251]
	v_pk_mul_f32 v[244:245], v[244:245], v[182:183]
	v_pk_mul_f32 v[246:247], v[246:247], v[154:155]
	v_pk_mul_f32 v[240:241], v[240:241], v[76:77]
	v_pk_mul_f32 v[242:243], v[242:243], v[78:79]
	v_pk_mul_f32 v[244:245], v[244:245], v[80:81]
	v_pk_mul_f32 v[246:247], v[246:247], v[82:83]
	v_cvt_pk_bf16_f32 v248, v240, v241
	v_cvt_pk_bf16_f32 v249, v242, v243
	v_cvt_pk_bf16_f32 v250, v244, v245
	v_cvt_pk_bf16_f32 v251, v246, v247
	global_store_dwordx4 v153, v[248:251], s[0:1]
	s_add_u32 s0, s0, 0x2c000
	s_addc_u32 s1, s1, 0
	v_pk_fma_f32 v[240:241], v[200:201], v[4:5], v[208:209]
	v_pk_fma_f32 v[242:243], v[202:203], v[6:7], v[210:211]
; DEV float bf2f(u16 h) { return __uint_as_float(((uint32_t)h) << 16); }
; DEV void gemm_tile(const u16* __restrict__ A, const u16* __restrict__ Bt, u16* __restrict__ C, int N, int K,
;                    int brow, int bcol, unsigned char* smem, int epi, const GateEpi& ge) {
;     ...
; #pragma unroll
;     for (int ai = 0; ai < 2; ++ai)
; #pragma unroll
;       for (int m = 0; m < 4; ++m) {
;         const int R0 = ai * 128 + wr * 64 + m * 16 + fq2 * 4;
; #pragma unroll
;         for (int n = 0; n < 2; ++n) {
;           const int cl = wc * 32 + n * 16 + fr2, cg = pn * 128 + cl;
;           float am2 = 0.f, am1 = 0.f;
;           if (R0 > 0) { am2 = bf2f(sAt[(R0 - 2) * AS + cl]); am1 = bf2f(sAt[(R0 - 1) * AS + cl]); }
; #pragma unroll
;           for (int j = 0; j < 4; ++j) {
;             const float a0 = acc[ai][0][m][n][j], b0 = acc[ai][1][m][n][j];
;             if (R0 > 0 || j >= 2) {
;               const float gv = gelu_tanh(bs[n] + w0[n] * am2 + w1[n] * am1 + w2[n] * a0) * b0;
;               ge.g[(size_t)(brow + R0 + j) * DFF + cg] = f2bf(gv);
;             } else {
;               ge.first_a[((size_t)pm * 2 + j) * DFF + cg] = sAt[(R0 + j) * AS + cl];
;               ge.first_b[((size_t)pm * 2 + j) * DFF + cg] = f2bf(b0);
;             }
;             if (R0 == 252 && j >= 2) ge.halo_a[((size_t)pm * 2 + (j - 2)) * DFF + cg] = sAt[(R0 + j) * AS + cl];
;             am2 = am1; am1 = a0;
;           }
;         }
;         __builtin_amdgcn_sched_barrier(0);
;       }
	v_pk_fma_f32 v[244:245], v[204:205], v[0:1], v[212:213]
	v_pk_fma_f32 v[246:247], v[206:207], v[2:3], v[214:215]
	v_fmac_f32_dpp v240, v4, v192 row_shr:1 row_mask:0xf bank_mask:0xf
	v_fmac_f32_dpp v241, v5, v193 row_shr:1 row_mask:0xf bank_mask:0xf
	v_fmac_f32_dpp v242, v6, v194 row_shr:1 row_mask:0xf bank_mask:0xf
	v_fmac_f32_dpp v243, v7, v195 row_shr:1 row_mask:0xf bank_mask:0xf
	v_fmac_f32_dpp v244, v0, v196 row_shr:1 row_mask:0xf bank_mask:0xf
	v_fmac_f32_dpp v245, v1, v197 row_shr:1 row_mask:0xf bank_mask:0xf
	v_fmac_f32_dpp v246, v2, v198 row_shr:1 row_mask:0xf bank_mask:0xf
	v_fmac_f32_dpp v247, v3, v199 row_shr:1 row_mask:0xf bank_mask:0xf
	v_fmac_f32_dpp v240, v12, v216 row_ror:1 row_mask:0xf bank_mask:0xf
	v_fmac_f32_dpp v241, v13, v217 row_ror:1 row_mask:0xf bank_mask:0xf
	v_fmac_f32_dpp v242, v14, v218 row_ror:1 row_mask:0xf bank_mask:0xf
	v_fmac_f32_dpp v243, v15, v219 row_ror:1 row_mask:0xf bank_mask:0xf
	v_fmac_f32_dpp v244, v8, v220 row_ror:1 row_mask:0xf bank_mask:0xf
	v_fmac_f32_dpp v245, v9, v221 row_ror:1 row_mask:0xf bank_mask:0xf
	v_fmac_f32_dpp v246, v10, v222 row_ror:1 row_mask:0xf bank_mask:0xf
	v_fmac_f32_dpp v247, v11, v223 row_ror:1 row_mask:0xf bank_mask:0xf
	v_fmac_f32_dpp v240, v4, v184 row_shr:2 row_mask:0xf bank_mask:0xf
	v_fmac_f32_dpp v241, v5, v185 row_shr:2 row_mask:0xf bank_mask:0xf
	v_fmac_f32_dpp v242, v6, v186 row_shr:2 row_mask:0xf bank_mask:0xf
	v_fmac_f32_dpp v243, v7, v187 row_shr:2 row_mask:0xf bank_mask:0xf
	v_fmac_f32_dpp v244, v0, v188 row_shr:2 row_mask:0xf bank_mask:0xf
	v_fmac_f32_dpp v245, v1, v189 row_shr:2 row_mask:0xf bank_mask:0xf
	v_fmac_f32_dpp v246, v2, v190 row_shr:2 row_mask:0xf bank_mask:0xf
	v_fmac_f32_dpp v247, v3, v191 row_shr:2 row_mask:0xf bank_mask:0xf
	v_fmac_f32_dpp v240, v12, v224 row_ror:2 row_mask:0xf bank_mask:0xf
	v_fmac_f32_dpp v241, v13, v225 row_ror:2 row_mask:0xf bank_mask:0xf
	v_fmac_f32_dpp v242, v14, v226 row_ror:2 row_mask:0xf bank_mask:0xf
	v_fmac_f32_dpp v243, v15, v227 row_ror:2 row_mask:0xf bank_mask:0xf
	v_fmac_f32_dpp v244, v8, v228 row_ror:2 row_mask:0xf bank_mask:0xf
	v_fmac_f32_dpp v245, v9, v229 row_ror:2 row_mask:0xf bank_mask:0xf
	v_fmac_f32_dpp v246, v10, v230 row_ror:2 row_mask:0xf bank_mask:0xf
	v_fmac_f32_dpp v247, v11, v231 row_ror:2 row_mask:0xf bank_mask:0xf
	v_fmac_f32_dpp v157, v12, v224 row_shr:1 row_mask:0xf bank_mask:0xf
	v_fmac_f32_dpp v157, v13, v225 row_shr:1 row_mask:0xf bank_mask:0xf
	v_fmac_f32_dpp v157, v14, v226 row_shr:1 row_mask:0xf bank_mask:0xf
	v_fmac_f32_dpp v157, v15, v227 row_shr:1 row_mask:0xf bank_mask:0xf
	v_fmac_f32_dpp v157, v8, v228 row_shr:1 row_mask:0xf bank_mask:0xf
	v_fmac_f32_dpp v157, v9, v229 row_shr:1 row_mask:0xf bank_mask:0xf
	v_fmac_f32_dpp v157, v10, v230 row_shr:1 row_mask:0xf bank_mask:0xf
	v_fmac_f32_dpp v157, v11, v231 row_shr:1 row_mask:0xf bank_mask:0xf
	v_fmac_f32_dpp v157, v12, v224 row_shr:1 row_mask:0xf bank_mask:0xf
	v_fmac_f32_dpp v157, v13, v225 row_shr:1 row_mask:0xf bank_mask:0xf
	v_fmac_f32_dpp v157, v14, v226 row_shr:1 row_mask:0xf bank_mask:0xf
	v_fmac_f32_dpp v157, v15, v227 row_shr:1 row_mask:0xf bank_mask:0xf
	v_fmac_f32_dpp v157, v8, v228 row_shr:1 row_mask:0xf bank_mask:0xf
	v_fmac_f32_dpp v157, v9, v229 row_shr:1 row_mask:0xf bank_mask:0xf
	v_fmac_f32_dpp v157, v10, v230 row_shr:1 row_mask:0xf bank_mask:0xf
	v_fmac_f32_dpp v157, v11, v231 row_shr:1 row_mask:0xf bank_mask:0xf
	v_fmac_f32_dpp v157, v12, v224 row_shr:1 row_mask:0xf bank_mask:0xf
	v_fmac_f32_dpp v157, v13, v225 row_shr:1 row_mask:0xf bank_mask:0xf
	v_fmac_f32_dpp v157, v14, v226 row_shr:1 row_mask:0xf bank_mask:0xf
	v_fmac_f32_dpp v157, v15, v227 row_shr:1 row_mask:0xf bank_mask:0xf
	v_fmac_f32_dpp v157, v8, v228 row_shr:1 row_mask:0xf bank_mask:0xf
	v_fmac_f32_dpp v157, v9, v229 row_shr:1 row_mask:0xf bank_mask:0xf
	v_fmac_f32_dpp v157, v10, v230 row_shr:1 row_mask:0xf bank_mask:0xf
	v_fmac_f32_dpp v157, v11, v231 row_shr:1 row_mask:0xf bank_mask:0xf
	v_fmac_f32_dpp v157, v12, v224 row_shr:1 row_mask:0xf bank_mask:0xf
	v_fmac_f32_dpp v157, v13, v225 row_shr:1 row_mask:0xf bank_mask:0xf
	v_fmac_f32_dpp v157, v14, v226 row_shr:1 row_mask:0xf bank_mask:0xf
	v_fmac_f32_dpp v157, v15, v227 row_shr:1 row_mask:0xf bank_mask:0xf
	v_fmac_f32_dpp v157, v8, v228 row_shr:1 row_mask:0xf bank_mask:0xf
	v_fmac_f32_dpp v157, v9, v229 row_shr:1 row_mask:0xf bank_mask:0xf
	v_fmac_f32_dpp v157, v10, v230 row_shr:1 row_mask:0xf bank_mask:0xf
	v_fmac_f32_dpp v157, v11, v231 row_shr:1 row_mask:0xf bank_mask:0xf
	v_pk_mul_f32 v[248:249], v[240:241], v[240:241]
	v_pk_mul_f32 v[250:251], v[242:243], v[242:243]
	v_pk_mul_f32 v[182:183], v[244:245], v[244:245]
	v_pk_mul_f32 v[154:155], v[246:247], v[246:247]
	v_pk_fma_f32 v[248:249], v[248:249], s[52:53], v[180:181]
	v_pk_fma_f32 v[250:251], v[250:251], s[52:53], v[180:181]
	v_pk_fma_f32 v[182:183], v[182:183], s[52:53], v[180:181]
	v_pk_fma_f32 v[154:155], v[154:155], s[52:53], v[180:181]
	v_pk_mul_f32 v[248:249], v[240:241], v[248:249]
	v_pk_mul_f32 v[250:251], v[242:243], v[250:251]
	v_pk_mul_f32 v[182:183], v[244:245], v[182:183]
	v_pk_mul_f32 v[154:155], v[246:247], v[154:155]
	v_exp_f32_e32 v248, v248
	v_exp_f32_e32 v249, v249
	v_exp_f32_e32 v250, v250
	v_exp_f32_e32 v251, v251
	v_exp_f32_e32 v182, v182
	v_exp_f32_e32 v183, v183
	v_exp_f32_e32 v154, v154
	v_exp_f32_e32 v155, v155
	v_pk_add_f32 v[248:249], v[248:249], s[94:95]
	v_pk_add_f32 v[250:251], v[250:251], s[94:95]
	v_pk_add_f32 v[182:183], v[182:183], s[94:95]
	v_pk_add_f32 v[154:155], v[154:155], s[94:95]
	v_rcp_f32_e32 v248, v248
	v_rcp_f32_e32 v249, v249
	v_rcp_f32_e32 v250, v250
	v_rcp_f32_e32 v251, v251
	v_rcp_f32_e32 v182, v182
	v_rcp_f32_e32 v183, v183
	v_rcp_f32_e32 v154, v154
	v_rcp_f32_e32 v155, v155
	v_pk_mul_f32 v[240:241], v[240:241], v[248:249]
	v_pk_mul_f32 v[242:243], v[242:243], v[250:251]
	v_pk_mul_f32 v[244:245], v[244:245], v[182:183]
	v_pk_mul_f32 v[246:247], v[246:247], v[154:155]
	v_pk_mul_f32 v[240:241], v[240:241], v[88:89]
	v_pk_mul_f32 v[242:243], v[242:243], v[90:91]
	v_pk_mul_f32 v[244:245], v[244:245], v[92:93]
	v_pk_mul_f32 v[246:247], v[246:247], v[94:95]
	v_cvt_pk_bf16_f32 v248, v240, v241
	v_cvt_pk_bf16_f32 v249, v242, v243
	v_cvt_pk_bf16_f32 v250, v244, v245
	v_cvt_pk_bf16_f32 v251, v246, v247
	global_store_dwordx4 v153, v[248:251], s[0:1]
	s_cmp_lg_u32 s34, 1
	s_cbranch_scc1 .Lgate_end_0
	s_mov_b32 exec_lo, 0xc000c000
	s_mov_b32 exec_hi, 0xc000c000
	v_cvt_pk_bf16_f32 v240, v4, v5
	v_cvt_pk_bf16_f32 v241, v6, v7
	v_cvt_pk_bf16_f32 v242, v0, v1
	v_cvt_pk_bf16_f32 v243, v2, v3
	global_store_dwordx4 v153, v[240:243], s[54:55]
	s_mov_b64 exec, -1
